# v26_align
# speedup vs baseline: 1.0172x; 1.0172x over previous
; #define PG8_STAGE(bufoff, gbase, voff) do { const __amdgpu_buffer_rsrc_t _rs = __builtin_amdgcn_make_buffer_rsrc((void*)(gbase), 0, 0x7fffffff, 0x00020000); _Pragma("unroll") for (int _i = 0; _i < 2; ++_i) \
;         __builtin_amdgcn_raw_ptr_buffer_load_lds(_rs, (LAS unsigned*)(lds + (bufoff) + ldsw + _i * 8192), 16, (int)(voff)[_i], 0, 0, 0); } while (0)
; #define PG8_WAIT_V(n) asm volatile("s_waitcnt vmcnt(" #n ")" ::: "memory")
; #define PG8_WAIT_L(n) asm volatile("s_waitcnt lgkmcnt(" #n ")" ::: "memory")
; #define PG8_BAR __builtin_amdgcn_s_barrier()
; #define PG8_SCHED __builtin_amdgcn_sched_barrier(0)
; template <class Epi, class Sched, bool F8 = false>
; __device__ __forceinline__ void gemm_phase(LAS unsigned char* lds, const int lda, const int ldb, const Sched& S, const Epi& E) {
;     ...
;             PG8_LDB(B0, 0, 0); PG8_LDB(B1, 0, 1); PG8_SCHED; PG8_LDA(At, 0, 0); PG8_STAGE(PG8_SA(1, 1), a1 + hstepA, voffA);
;             PG8_WAIT_V(8); PG8_WAIT_L(0); PG8_BAR; PG8_MMA(0, 0, At, B0); PG8_MMA(0, 1, At, B1); PG8_BAR; PG8_SCHED;
;             PG8_LDA(At, 0, 1); PG8_STAGE(PG8_SB(0, 0), b2, voffB); PG8_STAGE(PG8_SB(0, 1), b2 + hstepB, voffB); PG8_STAGE(PG8_SA(0, 0), a2, voffA);
;             PG8_WAIT_V(8); PG8_WAIT_L(0); PG8_BAR; PG8_MMA(1, 0, At, B0); PG8_MMA(1, 1, At, B1); PG8_BAR; PG8_SCHED;
.LBB0_116:
	ds_read_b128 v[132:135], v140
	ds_read_b128 v[146:149], v140 offset:1024
	ds_read_b128 v[150:153], v140 offset:2048
	ds_read_b128 v[154:157], v140 offset:3072
	ds_read_b128 v[158:161], v141
	ds_read_b128 v[162:165], v141 offset:1024
	ds_read_b128 v[166:169], v141 offset:2048
	ds_read_b128 v[174:177], v141 offset:3072
	s_add_u32 s16, s63, 0xfff00080
	s_addc_u32 s17, s67, -1
	s_cmp_eq_u32 s69, 60
	s_cselect_b32 s28, s70, s16
	s_cselect_b32 s23, s71, s17
	s_cselect_b32 s22, s73, s62
	s_cselect_b32 s24, s72, s7
	s_add_u32 s20, s28, 0x80
	s_addc_u32 s21, s23, 0
	s_and_b32 s17, s67, 0xffff
	s_mov_b32 s16, s63
	s_mov_b32 m0, s93
	ds_read_b128 v[178:181], v142
	ds_read_b128 v[182:185], v142 offset:1024
	ds_read_b128 v[186:189], v142 offset:2048
	ds_read_b128 v[190:193], v142 offset:3072
	ds_read_b128 v[194:197], v142 offset:4096
	ds_read_b128 v[198:201], v142 offset:5120
	ds_read_b128 v[202:205], v142 offset:6144
	ds_read_b128 v[206:209], v142 offset:7168
	buffer_load_dwordx4 v136, s[16:19], 0 offen lds
	s_mov_b32 m0, s94
	s_nop 0
	buffer_load_dwordx4 v138, s[16:19], 0 offen lds
	s_waitcnt vmcnt(8)
	s_waitcnt lgkmcnt(0)
	s_barrier
	s_setprio 1
	v_mfma_f32_16x16x32_bf16 v[124:127], v[132:135], v[178:181], v[124:127]
	v_mfma_f32_16x16x32_bf16 v[120:123], v[150:153], v[178:181], v[120:123]
	v_mfma_f32_16x16x32_bf16 v[108:111], v[132:135], v[186:189], v[108:111]
	v_mfma_f32_16x16x32_bf16 v[104:107], v[150:153], v[186:189], v[104:107]
	v_mfma_f32_16x16x32_bf16 v[92:95], v[132:135], v[194:197], v[92:95]
	v_mfma_f32_16x16x32_bf16 v[88:91], v[150:153], v[194:197], v[88:91]
	v_mfma_f32_16x16x32_bf16 v[76:79], v[132:135], v[202:205], v[76:79]
	v_mfma_f32_16x16x32_bf16 v[72:75], v[150:153], v[202:205], v[72:75]
	v_mfma_f32_16x16x32_bf16 v[124:127], v[146:149], v[182:185], v[124:127]
	v_mfma_f32_16x16x32_bf16 v[120:123], v[154:157], v[182:185], v[120:123]
	v_mfma_f32_16x16x32_bf16 v[108:111], v[146:149], v[190:193], v[108:111]
	v_mfma_f32_16x16x32_bf16 v[104:107], v[154:157], v[190:193], v[104:107]
	v_mfma_f32_16x16x32_bf16 v[92:95], v[146:149], v[198:201], v[92:95]
	v_mfma_f32_16x16x32_bf16 v[88:91], v[154:157], v[198:201], v[88:91]
	v_mfma_f32_16x16x32_bf16 v[76:79], v[146:149], v[206:209], v[76:79]
	v_mfma_f32_16x16x32_bf16 v[72:75], v[154:157], v[206:209], v[72:75]
	s_setprio 0
	s_setprio 1
	v_mfma_f32_16x16x32_bf16 v[116:119], v[158:161], v[178:181], v[116:119]
	v_mfma_f32_16x16x32_bf16 v[112:115], v[166:169], v[178:181], v[112:115]
	v_mfma_f32_16x16x32_bf16 v[100:103], v[158:161], v[186:189], v[100:103]
	v_mfma_f32_16x16x32_bf16 v[96:99], v[166:169], v[186:189], v[96:99]
	v_mfma_f32_16x16x32_bf16 v[84:87], v[158:161], v[194:197], v[84:87]
	v_mfma_f32_16x16x32_bf16 v[80:83], v[166:169], v[194:197], v[80:83]
	v_mfma_f32_16x16x32_bf16 v[68:71], v[158:161], v[202:205], v[68:71]
	v_mfma_f32_16x16x32_bf16 v[64:67], v[166:169], v[202:205], v[64:67]
	v_mfma_f32_16x16x32_bf16 v[116:119], v[162:165], v[182:185], v[116:119]
	v_mfma_f32_16x16x32_bf16 v[112:115], v[174:177], v[182:185], v[112:115]
	v_mfma_f32_16x16x32_bf16 v[100:103], v[162:165], v[190:193], v[100:103]
	v_mfma_f32_16x16x32_bf16 v[96:99], v[174:177], v[190:193], v[96:99]
	v_mfma_f32_16x16x32_bf16 v[84:87], v[162:165], v[198:201], v[84:87]
	v_mfma_f32_16x16x32_bf16 v[80:83], v[174:177], v[198:201], v[80:83]
	v_mfma_f32_16x16x32_bf16 v[68:71], v[162:165], v[206:209], v[68:71]
	v_mfma_f32_16x16x32_bf16 v[64:67], v[174:177], v[206:209], v[64:67]
	s_setprio 0
	s_barrier
	s_and_b32 s25, s22, 0xffff
	s_mov_b32 m0, s8
	s_mov_b32 s26, s18
	s_mov_b32 s27, s19
	s_add_u32 s16, s24, 0x4000
	ds_read_b128 v[178:181], v142 offset:16384
	ds_read_b128 v[182:185], v142 offset:17408
	ds_read_b128 v[186:189], v142 offset:18432
	ds_read_b128 v[190:193], v142 offset:19456
	ds_read_b128 v[194:197], v142 offset:20480
	ds_read_b128 v[198:201], v142 offset:21504
	ds_read_b128 v[202:205], v142 offset:22528
	ds_read_b128 v[206:209], v142 offset:23552
	buffer_load_dwordx4 v137, s[24:27], 0 offen lds
	s_mov_b32 m0, s9
	s_addc_u32 s17, s22, 0
	buffer_load_dwordx4 v139, s[24:27], 0 offen lds
	s_and_b32 s17, s17, 0xffff
	s_mov_b32 m0, s76
	s_and_b32 s29, s23, 0xffff
	buffer_load_dwordx4 v137, s[16:19], 0 offen lds
	s_mov_b32 m0, s79
	s_mov_b32 s30, s18
	buffer_load_dwordx4 v139, s[16:19], 0 offen lds
	s_mov_b32 s31, s19
	s_mov_b32 m0, s3
	s_nop 0
	buffer_load_dwordx4 v136, s[28:31], 0 offen lds
	s_mov_b32 m0, s80
	s_nop 0
	buffer_load_dwordx4 v138, s[28:31], 0 offen lds
	s_nop 0
	s_waitcnt vmcnt(8)
	s_waitcnt lgkmcnt(0)
	s_barrier
; #define PG8_STAGE(bufoff, gbase, voff) do { const __amdgpu_buffer_rsrc_t _rs = __builtin_amdgcn_make_buffer_rsrc((void*)(gbase), 0, 0x7fffffff, 0x00020000); _Pragma("unroll") for (int _i = 0; _i < 2; ++_i) \
;         __builtin_amdgcn_raw_ptr_buffer_load_lds(_rs, (LAS unsigned*)(lds + (bufoff) + ldsw + _i * 8192), 16, (int)(voff)[_i], 0, 0, 0); } while (0)
; #define PG8_WAIT_V(n) asm volatile("s_waitcnt vmcnt(" #n ")" ::: "memory")
; #define PG8_WAIT_L(n) asm volatile("s_waitcnt lgkmcnt(" #n ")" ::: "memory")
; #define PG8_BAR __builtin_amdgcn_s_barrier()
; #define PG8_SCHED __builtin_amdgcn_sched_barrier(0)
; template <class Epi, class Sched, bool F8 = false>
; __device__ __forceinline__ void gemm_phase(LAS unsigned char* lds, const int lda, const int ldb, const Sched& S, const Epi& E) {
;     ...
;             PG8_WAIT_V(8); PG8_WAIT_L(0); PG8_BAR; PG8_MMA(1, 0, At, B0); PG8_MMA(1, 1, At, B1); PG8_BAR; PG8_SCHED;
;             PG8_LDB(B0, 1, 0); PG8_LDB(B1, 1, 1); PG8_SCHED; PG8_LDA(At, 1, 0); PG8_STAGE(PG8_SA(0, 1), a2 + hstepA, voffA);
;             PG8_WAIT_V(8); PG8_WAIT_L(0); PG8_BAR; PG8_MMA(0, 0, At, B0); PG8_MMA(0, 1, At, B1); PG8_BAR; PG8_SCHED;
	s_setprio 1
	v_mfma_f32_16x16x32_bf16 v[60:63], v[132:135], v[178:181], v[60:63]
	v_mfma_f32_16x16x32_bf16 v[56:59], v[150:153], v[178:181], v[56:59]
	v_mfma_f32_16x16x32_bf16 v[44:47], v[132:135], v[186:189], v[44:47]
	v_mfma_f32_16x16x32_bf16 v[40:43], v[150:153], v[186:189], v[40:43]
	v_mfma_f32_16x16x32_bf16 v[28:31], v[132:135], v[194:197], v[28:31]
	v_mfma_f32_16x16x32_bf16 v[24:27], v[150:153], v[194:197], v[24:27]
	v_mfma_f32_16x16x32_bf16 v[12:15], v[132:135], v[202:205], v[12:15]
	v_mfma_f32_16x16x32_bf16 v[8:11], v[150:153], v[202:205], v[8:11]
	v_mfma_f32_16x16x32_bf16 v[60:63], v[146:149], v[182:185], v[60:63]
	v_mfma_f32_16x16x32_bf16 v[56:59], v[154:157], v[182:185], v[56:59]
	v_mfma_f32_16x16x32_bf16 v[44:47], v[146:149], v[190:193], v[44:47]
	v_mfma_f32_16x16x32_bf16 v[40:43], v[154:157], v[190:193], v[40:43]
	v_mfma_f32_16x16x32_bf16 v[28:31], v[146:149], v[198:201], v[28:31]
	v_mfma_f32_16x16x32_bf16 v[24:27], v[154:157], v[198:201], v[24:27]
	v_mfma_f32_16x16x32_bf16 v[12:15], v[146:149], v[206:209], v[12:15]
	v_mfma_f32_16x16x32_bf16 v[8:11], v[154:157], v[206:209], v[8:11]
	s_setprio 0
	s_setprio 1
	v_mfma_f32_16x16x32_bf16 v[52:55], v[158:161], v[178:181], v[52:55]
	v_mfma_f32_16x16x32_bf16 v[48:51], v[166:169], v[178:181], v[48:51]
	v_mfma_f32_16x16x32_bf16 v[36:39], v[158:161], v[186:189], v[36:39]
	v_mfma_f32_16x16x32_bf16 v[32:35], v[166:169], v[186:189], v[32:35]
	v_mfma_f32_16x16x32_bf16 v[20:23], v[158:161], v[194:197], v[20:23]
	v_mfma_f32_16x16x32_bf16 v[16:19], v[166:169], v[194:197], v[16:19]
	v_mfma_f32_16x16x32_bf16 v[4:7], v[158:161], v[202:205], v[4:7]
	v_mfma_f32_16x16x32_bf16 v[0:3], v[166:169], v[202:205], v[0:3]
	v_mfma_f32_16x16x32_bf16 v[52:55], v[162:165], v[182:185], v[52:55]
	v_mfma_f32_16x16x32_bf16 v[48:51], v[174:177], v[182:185], v[48:51]
	v_mfma_f32_16x16x32_bf16 v[36:39], v[162:165], v[190:193], v[36:39]
	v_mfma_f32_16x16x32_bf16 v[32:35], v[174:177], v[190:193], v[32:35]
	v_mfma_f32_16x16x32_bf16 v[20:23], v[162:165], v[198:201], v[20:23]
	v_mfma_f32_16x16x32_bf16 v[16:19], v[174:177], v[198:201], v[16:19]
	v_mfma_f32_16x16x32_bf16 v[4:7], v[162:165], v[206:209], v[4:7]
	v_mfma_f32_16x16x32_bf16 v[0:3], v[174:177], v[206:209], v[0:3]
	s_setprio 0
	s_barrier
	ds_read_b128 v[132:135], v143
	ds_read_b128 v[146:149], v143 offset:1024
	ds_read_b128 v[150:153], v143 offset:2048
	ds_read_b128 v[154:157], v143 offset:3072
	ds_read_b128 v[158:161], v144
	ds_read_b128 v[162:165], v144 offset:1024
	ds_read_b128 v[166:169], v144 offset:2048
	ds_read_b128 v[174:177], v144 offset:3072
	s_add_u32 s16, s28, 0x100000
	s_addc_u32 s17, s23, 0
	s_and_b32 s17, s17, 0xffff
	s_mov_b32 m0, s81
	ds_read_b128 v[178:181], v142 offset:32768
	ds_read_b128 v[182:185], v142 offset:33792
	ds_read_b128 v[186:189], v142 offset:34816
	ds_read_b128 v[190:193], v142 offset:35840
	ds_read_b128 v[194:197], v142 offset:36864
	ds_read_b128 v[198:201], v142 offset:37888
	ds_read_b128 v[202:205], v142 offset:38912
	ds_read_b128 v[206:209], v142 offset:39936
	buffer_load_dwordx4 v136, s[16:19], 0 offen lds
	s_mov_b32 m0, s82
	s_nop 0
	buffer_load_dwordx4 v138, s[16:19], 0 offen lds
	s_waitcnt vmcnt(8)
	s_waitcnt lgkmcnt(0)
	s_barrier
	s_setprio 1
	v_mfma_f32_16x16x32_bf16 v[124:127], v[132:135], v[178:181], v[124:127]
	v_mfma_f32_16x16x32_bf16 v[120:123], v[150:153], v[178:181], v[120:123]
	v_mfma_f32_16x16x32_bf16 v[108:111], v[132:135], v[186:189], v[108:111]
	v_mfma_f32_16x16x32_bf16 v[104:107], v[150:153], v[186:189], v[104:107]
	v_mfma_f32_16x16x32_bf16 v[92:95], v[132:135], v[194:197], v[92:95]
	v_mfma_f32_16x16x32_bf16 v[88:91], v[150:153], v[194:197], v[88:91]
	v_mfma_f32_16x16x32_bf16 v[76:79], v[132:135], v[202:205], v[76:79]
	v_mfma_f32_16x16x32_bf16 v[72:75], v[150:153], v[202:205], v[72:75]
	v_mfma_f32_16x16x32_bf16 v[124:127], v[146:149], v[182:185], v[124:127]
	v_mfma_f32_16x16x32_bf16 v[120:123], v[154:157], v[182:185], v[120:123]
	v_mfma_f32_16x16x32_bf16 v[108:111], v[146:149], v[190:193], v[108:111]
	v_mfma_f32_16x16x32_bf16 v[104:107], v[154:157], v[190:193], v[104:107]
	v_mfma_f32_16x16x32_bf16 v[92:95], v[146:149], v[198:201], v[92:95]
	v_mfma_f32_16x16x32_bf16 v[88:91], v[154:157], v[198:201], v[88:91]
	v_mfma_f32_16x16x32_bf16 v[76:79], v[146:149], v[206:209], v[76:79]
	v_mfma_f32_16x16x32_bf16 v[72:75], v[154:157], v[206:209], v[72:75]
	s_setprio 0
	s_setprio 1
	v_mfma_f32_16x16x32_bf16 v[116:119], v[158:161], v[178:181], v[116:119]
	v_mfma_f32_16x16x32_bf16 v[112:115], v[166:169], v[178:181], v[112:115]
	v_mfma_f32_16x16x32_bf16 v[100:103], v[158:161], v[186:189], v[100:103]
	v_mfma_f32_16x16x32_bf16 v[96:99], v[166:169], v[186:189], v[96:99]
	v_mfma_f32_16x16x32_bf16 v[84:87], v[158:161], v[194:197], v[84:87]
	v_mfma_f32_16x16x32_bf16 v[80:83], v[166:169], v[194:197], v[80:83]
	v_mfma_f32_16x16x32_bf16 v[68:71], v[158:161], v[202:205], v[68:71]
	v_mfma_f32_16x16x32_bf16 v[64:67], v[166:169], v[202:205], v[64:67]
	v_mfma_f32_16x16x32_bf16 v[116:119], v[162:165], v[182:185], v[116:119]
	v_mfma_f32_16x16x32_bf16 v[112:115], v[174:177], v[182:185], v[112:115]
	v_mfma_f32_16x16x32_bf16 v[100:103], v[162:165], v[190:193], v[100:103]
	v_mfma_f32_16x16x32_bf16 v[96:99], v[174:177], v[190:193], v[96:99]
	v_mfma_f32_16x16x32_bf16 v[84:87], v[162:165], v[198:201], v[84:87]
	v_mfma_f32_16x16x32_bf16 v[80:83], v[174:177], v[198:201], v[80:83]
	v_mfma_f32_16x16x32_bf16 v[68:71], v[162:165], v[206:209], v[68:71]
	v_mfma_f32_16x16x32_bf16 v[64:67], v[174:177], v[206:209], v[64:67]
	s_setprio 0
	s_barrier
; #define PG8_STAGE(bufoff, gbase, voff) do { const __amdgpu_buffer_rsrc_t _rs = __builtin_amdgcn_make_buffer_rsrc((void*)(gbase), 0, 0x7fffffff, 0x00020000); _Pragma("unroll") for (int _i = 0; _i < 2; ++_i) \
;         __builtin_amdgcn_raw_ptr_buffer_load_lds(_rs, (LAS unsigned*)(lds + (bufoff) + ldsw + _i * 8192), 16, (int)(voff)[_i], 0, 0, 0); } while (0)
; #define PG8_WAIT_V(n) asm volatile("s_waitcnt vmcnt(" #n ")" ::: "memory")
; #define PG8_WAIT_L(n) asm volatile("s_waitcnt lgkmcnt(" #n ")" ::: "memory")
; #define PG8_BAR __builtin_amdgcn_s_barrier()
; #define PG8_SCHED __builtin_amdgcn_sched_barrier(0)
; template <class Epi, class Sched, bool F8 = false>
; __device__ __forceinline__ void gemm_phase(LAS unsigned char* lds, const int lda, const int ldb, const Sched& S, const Epi& E) {
;     ...
;         for (int t = 0; t < nt; t += 2) {
;     ...
;             PG8_LDA(At, 1, 1); PG8_STAGE(PG8_SB(1, 0), b3, voffB); PG8_STAGE(PG8_SB(1, 1), b3 + hstepB, voffB); PG8_STAGE(PG8_SA(1, 0), a3, voffA);
;             PG8_WAIT_V(8); PG8_WAIT_L(0); PG8_BAR; PG8_MMA(1, 0, At, B0); PG8_MMA(1, 1, At, B1); PG8_BAR; PG8_SCHED;
	s_add_u32 s16, s24, 0x8000
	s_addc_u32 s17, s22, 0
	s_mov_b32 m0, s87
	s_and_b32 s17, s17, 0xffff
	ds_read_b128 v[178:181], v142 offset:49152
	ds_read_b128 v[182:185], v142 offset:50176
	ds_read_b128 v[186:189], v142 offset:51200
	ds_read_b128 v[190:193], v142 offset:52224
	ds_read_b128 v[194:197], v142 offset:53248
	ds_read_b128 v[198:201], v142 offset:54272
	ds_read_b128 v[202:205], v142 offset:55296
	ds_read_b128 v[206:209], v142 offset:56320
	buffer_load_dwordx4 v137, s[16:19], 0 offen lds
	s_mov_b32 m0, s88
	s_mov_b32 s23, s19
	buffer_load_dwordx4 v139, s[16:19], 0 offen lds
	s_add_u32 s16, s24, 0xc000
	s_addc_u32 s17, s22, 0
	s_and_b32 s17, s17, 0xffff
	s_mov_b32 m0, s91
	s_and_b32 s21, s21, 0xffff
	buffer_load_dwordx4 v137, s[16:19], 0 offen lds
	s_mov_b32 m0, s92
	s_mov_b32 s22, s18
	buffer_load_dwordx4 v139, s[16:19], 0 offen lds
	s_mov_b32 m0, s89
	s_nop 0
	buffer_load_dwordx4 v136, s[20:23], 0 offen lds
	s_mov_b32 m0, s90
	s_nop 0
	buffer_load_dwordx4 v138, s[20:23], 0 offen lds
	s_waitcnt vmcnt(8)
	s_waitcnt lgkmcnt(0)
	s_barrier
	s_setprio 1
	v_mfma_f32_16x16x32_bf16 v[60:63], v[132:135], v[178:181], v[60:63]
	v_mfma_f32_16x16x32_bf16 v[56:59], v[150:153], v[178:181], v[56:59]
	v_mfma_f32_16x16x32_bf16 v[44:47], v[132:135], v[186:189], v[44:47]
	v_mfma_f32_16x16x32_bf16 v[40:43], v[150:153], v[186:189], v[40:43]
	v_mfma_f32_16x16x32_bf16 v[28:31], v[132:135], v[194:197], v[28:31]
	v_mfma_f32_16x16x32_bf16 v[24:27], v[150:153], v[194:197], v[24:27]
	v_mfma_f32_16x16x32_bf16 v[12:15], v[132:135], v[202:205], v[12:15]
	v_mfma_f32_16x16x32_bf16 v[8:11], v[150:153], v[202:205], v[8:11]
	v_mfma_f32_16x16x32_bf16 v[60:63], v[146:149], v[182:185], v[60:63]
	v_mfma_f32_16x16x32_bf16 v[56:59], v[154:157], v[182:185], v[56:59]
	v_mfma_f32_16x16x32_bf16 v[44:47], v[146:149], v[190:193], v[44:47]
	v_mfma_f32_16x16x32_bf16 v[40:43], v[154:157], v[190:193], v[40:43]
	v_mfma_f32_16x16x32_bf16 v[28:31], v[146:149], v[198:201], v[28:31]
	v_mfma_f32_16x16x32_bf16 v[24:27], v[154:157], v[198:201], v[24:27]
	v_mfma_f32_16x16x32_bf16 v[12:15], v[146:149], v[206:209], v[12:15]
	v_mfma_f32_16x16x32_bf16 v[8:11], v[154:157], v[206:209], v[8:11]
	s_setprio 0
	s_setprio 1
	v_mfma_f32_16x16x32_bf16 v[52:55], v[158:161], v[178:181], v[52:55]
	v_mfma_f32_16x16x32_bf16 v[48:51], v[166:169], v[178:181], v[48:51]
	v_mfma_f32_16x16x32_bf16 v[36:39], v[158:161], v[186:189], v[36:39]
	v_mfma_f32_16x16x32_bf16 v[32:35], v[166:169], v[186:189], v[32:35]
	v_mfma_f32_16x16x32_bf16 v[20:23], v[158:161], v[194:197], v[20:23]
	v_mfma_f32_16x16x32_bf16 v[16:19], v[166:169], v[194:197], v[16:19]
	v_mfma_f32_16x16x32_bf16 v[4:7], v[158:161], v[202:205], v[4:7]
	v_mfma_f32_16x16x32_bf16 v[0:3], v[166:169], v[202:205], v[0:3]
	v_mfma_f32_16x16x32_bf16 v[52:55], v[162:165], v[182:185], v[52:55]
	v_mfma_f32_16x16x32_bf16 v[48:51], v[174:177], v[182:185], v[48:51]
	v_mfma_f32_16x16x32_bf16 v[36:39], v[162:165], v[190:193], v[36:39]
	v_mfma_f32_16x16x32_bf16 v[32:35], v[174:177], v[190:193], v[32:35]
	v_mfma_f32_16x16x32_bf16 v[20:23], v[162:165], v[198:201], v[20:23]
	v_mfma_f32_16x16x32_bf16 v[16:19], v[174:177], v[198:201], v[16:19]
	v_mfma_f32_16x16x32_bf16 v[4:7], v[162:165], v[206:209], v[4:7]
	v_mfma_f32_16x16x32_bf16 v[0:3], v[174:177], v[206:209], v[0:3]
	s_setprio 0
	s_barrier
	s_add_i32 s69, s69, 2
	s_add_u32 s7, s7, 0x10000
	s_addc_u32 s62, s62, 0
	s_add_u32 s63, s63, 0x100
	s_addc_u32 s67, s67, 0
	s_cmp_gt_u32 s69, 61
	s_cbranch_scc0 .LBB0_116
	s_and_b64 vcc, exec, s[38:39]
	s_cbranch_vccz .LBB0_119
	s_barrier

; #define PG8_STAGE(bufoff, gbase, voff) do { const __amdgpu_buffer_rsrc_t _rs = __builtin_amdgcn_make_buffer_rsrc((void*)(gbase), 0, 0x7fffffff, 0x00020000); _Pragma("unroll") for (int _i = 0; _i < 2; ++_i) \
;         __builtin_amdgcn_raw_ptr_buffer_load_lds(_rs, (LAS unsigned*)(lds + (bufoff) + ldsw + _i * 8192), 16, (int)(voff)[_i], 0, 0, 0); } while (0)
; #define PG8_WAIT_V(n) asm volatile("s_waitcnt vmcnt(" #n ")" ::: "memory")
; #define PG8_WAIT_L(n) asm volatile("s_waitcnt lgkmcnt(" #n ")" ::: "memory")
; #define PG8_BAR __builtin_amdgcn_s_barrier()
; #define PG8_SCHED __builtin_amdgcn_sched_barrier(0)
; template <class Epi, class Sched, bool F8 = false>
; __device__ __forceinline__ void gemm_phase(LAS unsigned char* lds, const int lda, const int ldb, const Sched& S, const Epi& E) {
;     ...
;             PG8_LDB(B0, 0, 0); PG8_LDB(B1, 0, 1); PG8_SCHED; PG8_LDA(At, 0, 0); PG8_STAGE(PG8_SA(1, 1), a1 + hstepA, voffA);
;             PG8_WAIT_V(8); PG8_WAIT_L(0); PG8_BAR; PG8_MMA(0, 0, At, B0); PG8_MMA(0, 1, At, B1); PG8_BAR; PG8_SCHED;
;             PG8_LDA(At, 0, 1); PG8_STAGE(PG8_SB(0, 0), b2, voffB); PG8_STAGE(PG8_SB(0, 1), b2 + hstepB, voffB); PG8_STAGE(PG8_SA(0, 0), a2, voffA);
;             PG8_WAIT_V(8); PG8_WAIT_L(0); PG8_BAR; PG8_MMA(1, 0, At, B0); PG8_MMA(1, 1, At, B1); PG8_BAR; PG8_SCHED;
.LBB0_174:
	ds_read_b128 v[146:149], v140
	ds_read_b128 v[150:153], v140 offset:1024
	ds_read_b128 v[154:157], v140 offset:2048
	ds_read_b128 v[158:161], v140 offset:3072
	ds_read_b128 v[162:165], v141
	ds_read_b128 v[166:169], v141 offset:1024
	ds_read_b128 v[174:177], v141 offset:2048
	ds_read_b128 v[178:181], v141 offset:3072
	s_add_u32 s16, s63, 0xfff80080
	s_addc_u32 s17, s67, -1
	s_cmp_eq_u32 s69, 28
	s_cselect_b32 s28, s70, s16
	s_cselect_b32 s23, s71, s17
	s_cselect_b32 s22, s73, s62
	s_cselect_b32 s24, s72, s7
	s_add_u32 s20, s28, 0x80
	s_addc_u32 s21, s23, 0
	s_and_b32 s17, s67, 0xffff
	s_mov_b32 s16, s63
	s_mov_b32 m0, s96
	ds_read_b128 v[182:185], v142
	ds_read_b128 v[186:189], v142 offset:1024
	ds_read_b128 v[190:193], v142 offset:2048
	ds_read_b128 v[194:197], v142 offset:3072
	ds_read_b128 v[198:201], v142 offset:4096
	ds_read_b128 v[202:205], v142 offset:5120
	ds_read_b128 v[206:209], v142 offset:6144
	ds_read_b128 v[210:213], v142 offset:7168
	buffer_load_dwordx4 v136, s[16:19], 0 offen lds
	s_mov_b32 m0, s97
	s_nop 0
	buffer_load_dwordx4 v138, s[16:19], 0 offen lds
	s_nop 0
	s_waitcnt vmcnt(8)
	s_waitcnt lgkmcnt(0)
	s_barrier
	s_setprio 1
	v_mfma_scale_f32_16x16x128_f8f6f4 v[124:127], v[146:153], v[182:189], v[124:127], v143, v143 op_sel_hi:[0,0,0]
	v_mfma_scale_f32_16x16x128_f8f6f4 v[120:123], v[154:161], v[182:189], v[120:123], v143, v143 op_sel_hi:[0,0,0]
	v_mfma_scale_f32_16x16x128_f8f6f4 v[108:111], v[146:153], v[190:197], v[108:111], v143, v143 op_sel_hi:[0,0,0]
	v_mfma_scale_f32_16x16x128_f8f6f4 v[104:107], v[154:161], v[190:197], v[104:107], v143, v143 op_sel_hi:[0,0,0]
	v_mfma_scale_f32_16x16x128_f8f6f4 v[132:135], v[146:153], v[198:205], v[92:95], v143, v143 op_sel_hi:[0,0,0]
	v_mfma_scale_f32_16x16x128_f8f6f4 v[214:217], v[154:161], v[198:205], v[88:91], v143, v143 op_sel_hi:[0,0,0]
	v_mfma_scale_f32_16x16x128_f8f6f4 v[218:221], v[146:153], v[206:213], v[76:79], v143, v143 op_sel_hi:[0,0,0]
	v_mfma_scale_f32_16x16x128_f8f6f4 v[222:225], v[154:161], v[206:213], v[72:75], v143, v143 op_sel_hi:[0,0,0]
	s_setprio 0
	s_setprio 1
	v_mfma_scale_f32_16x16x128_f8f6f4 v[116:119], v[162:169], v[182:189], v[116:119], v143, v143 op_sel_hi:[0,0,0]
	v_mfma_scale_f32_16x16x128_f8f6f4 v[112:115], v[174:181], v[182:189], v[112:115], v143, v143 op_sel_hi:[0,0,0]
	v_mfma_scale_f32_16x16x128_f8f6f4 v[100:103], v[162:169], v[190:197], v[100:103], v143, v143 op_sel_hi:[0,0,0]
	v_mfma_scale_f32_16x16x128_f8f6f4 v[96:99], v[174:181], v[190:197], v[96:99], v143, v143 op_sel_hi:[0,0,0]
	v_mfma_scale_f32_16x16x128_f8f6f4 v[182:185], v[162:169], v[198:205], v[84:87], v143, v143 op_sel_hi:[0,0,0]
	v_mfma_scale_f32_16x16x128_f8f6f4 v[186:189], v[174:181], v[198:205], v[80:83], v143, v143 op_sel_hi:[0,0,0]
	v_mfma_scale_f32_16x16x128_f8f6f4 v[190:193], v[162:169], v[206:213], v[68:71], v143, v143 op_sel_hi:[0,0,0]
	v_mfma_scale_f32_16x16x128_f8f6f4 v[194:197], v[174:181], v[206:213], v[64:67], v143, v143 op_sel_hi:[0,0,0]
	s_setprio 0
	s_barrier
	s_and_b32 s25, s22, 0xffff
	s_mov_b32 m0, s79
	s_mov_b32 s26, s18
	s_mov_b32 s27, s19
	s_add_u32 s16, s24, 0x4000
	ds_read_b128 v[64:67], v142 offset:16384
	ds_read_b128 v[68:71], v142 offset:17408
	ds_read_b128 v[72:75], v142 offset:18432
	ds_read_b128 v[76:79], v142 offset:19456
	ds_read_b128 v[80:83], v142 offset:20480
	ds_read_b128 v[84:87], v142 offset:21504
	ds_read_b128 v[88:91], v142 offset:22528
	ds_read_b128 v[92:95], v142 offset:23552
	buffer_load_dwordx4 v137, s[24:27], 0 offen lds
	s_mov_b32 m0, s80
	s_addc_u32 s17, s22, 0
	buffer_load_dwordx4 v139, s[24:27], 0 offen lds
	s_and_b32 s17, s17, 0xffff
	s_mov_b32 m0, s81
	s_and_b32 s29, s23, 0xffff
	buffer_load_dwordx4 v137, s[16:19], 0 offen lds
	s_mov_b32 m0, s82
	s_mov_b32 s30, s18
	buffer_load_dwordx4 v139, s[16:19], 0 offen lds
	s_mov_b32 s31, s19
	s_mov_b32 m0, s76
	s_nop 0
	buffer_load_dwordx4 v136, s[28:31], 0 offen lds
	s_mov_b32 m0, s83
	s_nop 0
	buffer_load_dwordx4 v138, s[28:31], 0 offen lds
	s_nop 0
	s_waitcnt vmcnt(8)
	s_waitcnt lgkmcnt(0)
	s_barrier
	s_setprio 1
	v_mfma_scale_f32_16x16x128_f8f6f4 v[60:63], v[146:153], v[64:71], v[60:63], v143, v143 op_sel_hi:[0,0,0]
	v_mfma_scale_f32_16x16x128_f8f6f4 v[56:59], v[154:161], v[64:71], v[56:59], v143, v143 op_sel_hi:[0,0,0]
	v_mfma_scale_f32_16x16x128_f8f6f4 v[198:201], v[146:153], v[72:79], v[44:47], v143, v143 op_sel_hi:[0,0,0]
	v_mfma_scale_f32_16x16x128_f8f6f4 v[202:205], v[154:161], v[72:79], v[40:43], v143, v143 op_sel_hi:[0,0,0]
	v_mfma_scale_f32_16x16x128_f8f6f4 v[206:209], v[146:153], v[80:87], v[28:31], v143, v143 op_sel_hi:[0,0,0]
	v_mfma_scale_f32_16x16x128_f8f6f4 v[210:213], v[154:161], v[80:87], v[24:27], v143, v143 op_sel_hi:[0,0,0]
	v_mfma_scale_f32_16x16x128_f8f6f4 v[226:229], v[146:153], v[88:95], v[12:15], v143, v143 op_sel_hi:[0,0,0]
	v_mfma_scale_f32_16x16x128_f8f6f4 v[230:233], v[154:161], v[88:95], v[8:11], v143, v143 op_sel_hi:[0,0,0]
	s_setprio 0
	s_setprio 1
	v_mfma_scale_f32_16x16x128_f8f6f4 v[52:55], v[162:169], v[64:71], v[52:55], v143, v143 op_sel_hi:[0,0,0]
	v_mfma_scale_f32_16x16x128_f8f6f4 v[48:51], v[174:181], v[64:71], v[48:51], v143, v143 op_sel_hi:[0,0,0]
	v_mfma_scale_f32_16x16x128_f8f6f4 v[234:237], v[162:169], v[72:79], v[36:39], v143, v143 op_sel_hi:[0,0,0]
	v_mfma_scale_f32_16x16x128_f8f6f4 v[238:241], v[174:181], v[72:79], v[32:35], v143, v143 op_sel_hi:[0,0,0]
	v_mfma_scale_f32_16x16x128_f8f6f4 v[242:245], v[162:169], v[80:87], v[20:23], v143, v143 op_sel_hi:[0,0,0]
	v_mfma_scale_f32_16x16x128_f8f6f4 v[246:249], v[174:181], v[80:87], v[16:19], v143, v143 op_sel_hi:[0,0,0]
	v_mfma_scale_f32_16x16x128_f8f6f4 v[250:253], v[162:169], v[88:95], v[4:7], v143, v143 op_sel_hi:[0,0,0]
	v_mfma_scale_f32_16x16x128_f8f6f4 v[170:173], v[174:181], v[88:95], v[0:3], v143, v143 op_sel_hi:[0,0,0]
	s_setprio 0
	s_barrier
; #define PG8_STAGE(bufoff, gbase, voff) do { const __amdgpu_buffer_rsrc_t _rs = __builtin_amdgcn_make_buffer_rsrc((void*)(gbase), 0, 0x7fffffff, 0x00020000); _Pragma("unroll") for (int _i = 0; _i < 2; ++_i) \
;         __builtin_amdgcn_raw_ptr_buffer_load_lds(_rs, (LAS unsigned*)(lds + (bufoff) + ldsw + _i * 8192), 16, (int)(voff)[_i], 0, 0, 0); } while (0)
; #define PG8_WAIT_V(n) asm volatile("s_waitcnt vmcnt(" #n ")" ::: "memory")
; #define PG8_WAIT_L(n) asm volatile("s_waitcnt lgkmcnt(" #n ")" ::: "memory")
; #define PG8_BAR __builtin_amdgcn_s_barrier()
; #define PG8_SCHED __builtin_amdgcn_sched_barrier(0)
; template <class Epi, class Sched, bool F8 = false>
; __device__ __forceinline__ void gemm_phase(LAS unsigned char* lds, const int lda, const int ldb, const Sched& S, const Epi& E) {
;     ...
;             PG8_LDB(B0, 1, 0); PG8_LDB(B1, 1, 1); PG8_SCHED; PG8_LDA(At, 1, 0); PG8_STAGE(PG8_SA(0, 1), a2 + hstepA, voffA);
;             PG8_WAIT_V(8); PG8_WAIT_L(0); PG8_BAR; PG8_MMA(0, 0, At, B0); PG8_MMA(0, 1, At, B1); PG8_BAR; PG8_SCHED;
;             PG8_LDA(At, 1, 1); PG8_STAGE(PG8_SB(1, 0), b3, voffB); PG8_STAGE(PG8_SB(1, 1), b3 + hstepB, voffB); PG8_STAGE(PG8_SA(1, 0), a3, voffA);
;             PG8_WAIT_V(8); PG8_WAIT_L(0); PG8_BAR; PG8_MMA(1, 0, At, B0); PG8_MMA(1, 1, At, B1); PG8_BAR; PG8_SCHED;
;     ...
;         }
;         if (wr == 0) PG8_BAR;
	s_nop 4
	ds_read_b128 v[0:3], v144
	ds_read_b128 v[4:7], v144 offset:1024
	ds_read_b128 v[16:19], v144 offset:2048
	ds_read_b128 v[20:23], v144 offset:3072
	ds_read_b128 v[146:149], v145
	ds_read_b128 v[150:153], v145 offset:1024
	ds_read_b128 v[154:157], v145 offset:2048
	ds_read_b128 v[158:161], v145 offset:3072
	s_add_u32 s16, s28, 0x80000
	s_addc_u32 s17, s23, 0
	s_and_b32 s17, s17, 0xffff
	s_mov_b32 m0, s84
	ds_read_b128 v[8:11], v142 offset:32768
	ds_read_b128 v[12:15], v142 offset:33792
	ds_read_b128 v[24:27], v142 offset:34816
	ds_read_b128 v[28:31], v142 offset:35840
	ds_read_b128 v[32:35], v142 offset:36864
	ds_read_b128 v[36:39], v142 offset:37888
	ds_read_b128 v[40:43], v142 offset:38912
	ds_read_b128 v[44:47], v142 offset:39936
	buffer_load_dwordx4 v136, s[16:19], 0 offen lds
	s_mov_b32 m0, s85
	s_nop 0
	buffer_load_dwordx4 v138, s[16:19], 0 offen lds
	s_nop 0
	s_waitcnt vmcnt(8)
	s_waitcnt lgkmcnt(0)
	s_barrier
	s_setprio 1
	v_mfma_scale_f32_16x16x128_f8f6f4 v[124:127], v[0:7], v[8:15], v[124:127], v143, v143 op_sel_hi:[0,0,0]
	v_mfma_scale_f32_16x16x128_f8f6f4 v[120:123], v[16:23], v[8:15], v[120:123], v143, v143 op_sel_hi:[0,0,0]
	v_mfma_scale_f32_16x16x128_f8f6f4 v[108:111], v[0:7], v[24:31], v[108:111], v143, v143 op_sel_hi:[0,0,0]
	v_mfma_scale_f32_16x16x128_f8f6f4 v[104:107], v[16:23], v[24:31], v[104:107], v143, v143 op_sel_hi:[0,0,0]
	v_mfma_scale_f32_16x16x128_f8f6f4 v[92:95], v[0:7], v[32:39], v[132:135], v143, v143 op_sel_hi:[0,0,0]
	v_mfma_scale_f32_16x16x128_f8f6f4 v[88:91], v[16:23], v[32:39], v[214:217], v143, v143 op_sel_hi:[0,0,0]
	v_mfma_scale_f32_16x16x128_f8f6f4 v[76:79], v[0:7], v[40:47], v[218:221], v143, v143 op_sel_hi:[0,0,0]
	v_mfma_scale_f32_16x16x128_f8f6f4 v[72:75], v[16:23], v[40:47], v[222:225], v143, v143 op_sel_hi:[0,0,0]
	s_setprio 0
	s_setprio 1
	v_mfma_scale_f32_16x16x128_f8f6f4 v[116:119], v[146:153], v[8:15], v[116:119], v143, v143 op_sel_hi:[0,0,0]
	v_mfma_scale_f32_16x16x128_f8f6f4 v[112:115], v[154:161], v[8:15], v[112:115], v143, v143 op_sel_hi:[0,0,0]
	v_mfma_scale_f32_16x16x128_f8f6f4 v[100:103], v[146:153], v[24:31], v[100:103], v143, v143 op_sel_hi:[0,0,0]
	v_mfma_scale_f32_16x16x128_f8f6f4 v[96:99], v[154:161], v[24:31], v[96:99], v143, v143 op_sel_hi:[0,0,0]
	v_mfma_scale_f32_16x16x128_f8f6f4 v[84:87], v[146:153], v[32:39], v[182:185], v143, v143 op_sel_hi:[0,0,0]
	v_mfma_scale_f32_16x16x128_f8f6f4 v[80:83], v[154:161], v[32:39], v[186:189], v143, v143 op_sel_hi:[0,0,0]
	v_mfma_scale_f32_16x16x128_f8f6f4 v[68:71], v[146:153], v[40:47], v[190:193], v143, v143 op_sel_hi:[0,0,0]
	v_mfma_scale_f32_16x16x128_f8f6f4 v[64:67], v[154:161], v[40:47], v[194:197], v143, v143 op_sel_hi:[0,0,0]
	s_setprio 0
	s_barrier
	s_add_u32 s16, s24, 0x8000
	s_addc_u32 s17, s22, 0
	s_mov_b32 m0, s90
	s_and_b32 s17, s17, 0xffff
	ds_read_b128 v[32:35], v142 offset:49152
	ds_read_b128 v[36:39], v142 offset:50176
	ds_read_b128 v[162:165], v142 offset:51200
	ds_read_b128 v[166:169], v142 offset:52224
	ds_read_b128 v[174:177], v142 offset:53248
	ds_read_b128 v[178:181], v142 offset:54272
	ds_read_b128 v[182:185], v142 offset:55296
	ds_read_b128 v[186:189], v142 offset:56320
	buffer_load_dwordx4 v137, s[16:19], 0 offen lds
	s_mov_b32 m0, s91
	s_mov_b32 s23, s19
	buffer_load_dwordx4 v139, s[16:19], 0 offen lds
	s_add_u32 s16, s24, 0xc000
	s_addc_u32 s17, s22, 0
	s_and_b32 s17, s17, 0xffff
	s_mov_b32 m0, s94
	s_and_b32 s21, s21, 0xffff
	buffer_load_dwordx4 v137, s[16:19], 0 offen lds
	s_mov_b32 m0, s95
	s_mov_b32 s22, s18
	buffer_load_dwordx4 v139, s[16:19], 0 offen lds
	s_mov_b32 m0, s92
	s_nop 0
	buffer_load_dwordx4 v136, s[20:23], 0 offen lds
	s_mov_b32 m0, s93
	s_nop 0
	buffer_load_dwordx4 v138, s[20:23], 0 offen lds
	s_waitcnt vmcnt(8)
	s_waitcnt lgkmcnt(0)
	s_barrier
	s_setprio 1
	v_mfma_scale_f32_16x16x128_f8f6f4 v[60:63], v[0:7], v[32:39], v[60:63], v143, v143 op_sel_hi:[0,0,0]
	v_mfma_scale_f32_16x16x128_f8f6f4 v[56:59], v[16:23], v[32:39], v[56:59], v143, v143 op_sel_hi:[0,0,0]
	v_mfma_scale_f32_16x16x128_f8f6f4 v[44:47], v[0:7], v[162:169], v[198:201], v143, v143 op_sel_hi:[0,0,0]
	v_mfma_scale_f32_16x16x128_f8f6f4 v[40:43], v[16:23], v[162:169], v[202:205], v143, v143 op_sel_hi:[0,0,0]
	v_mfma_scale_f32_16x16x128_f8f6f4 v[28:31], v[0:7], v[174:181], v[206:209], v143, v143 op_sel_hi:[0,0,0]
	v_mfma_scale_f32_16x16x128_f8f6f4 v[24:27], v[16:23], v[174:181], v[210:213], v143, v143 op_sel_hi:[0,0,0]
	v_mfma_scale_f32_16x16x128_f8f6f4 v[12:15], v[0:7], v[182:189], v[226:229], v143, v143 op_sel_hi:[0,0,0]
	v_mfma_scale_f32_16x16x128_f8f6f4 v[8:11], v[16:23], v[182:189], v[230:233], v143, v143 op_sel_hi:[0,0,0]
	s_setprio 0
	s_setprio 1
	v_mfma_scale_f32_16x16x128_f8f6f4 v[52:55], v[146:153], v[32:39], v[52:55], v143, v143 op_sel_hi:[0,0,0]
	v_mfma_scale_f32_16x16x128_f8f6f4 v[48:51], v[154:161], v[32:39], v[48:51], v143, v143 op_sel_hi:[0,0,0]
	v_mfma_scale_f32_16x16x128_f8f6f4 v[36:39], v[146:153], v[162:169], v[234:237], v143, v143 op_sel_hi:[0,0,0]
	v_mfma_scale_f32_16x16x128_f8f6f4 v[32:35], v[154:161], v[162:169], v[238:241], v143, v143 op_sel_hi:[0,0,0]
	v_mfma_scale_f32_16x16x128_f8f6f4 v[20:23], v[146:153], v[174:181], v[242:245], v143, v143 op_sel_hi:[0,0,0]
	v_mfma_scale_f32_16x16x128_f8f6f4 v[16:19], v[154:161], v[174:181], v[246:249], v143, v143 op_sel_hi:[0,0,0]
	v_mfma_scale_f32_16x16x128_f8f6f4 v[4:7], v[146:153], v[182:189], v[250:253], v143, v143 op_sel_hi:[0,0,0]
	v_mfma_scale_f32_16x16x128_f8f6f4 v[0:3], v[154:161], v[182:189], v[170:173], v143, v143 op_sel_hi:[0,0,0]
	s_setprio 0
	s_barrier
	s_add_i32 s69, s69, 2
	s_add_u32 s7, s7, 0x10000
	s_addc_u32 s62, s62, 0
	s_add_u32 s63, s63, 0x100
	s_addc_u32 s67, s67, 0
	s_cmp_gt_u32 s69, 29
	s_cbranch_scc0 .LBB0_174
	s_and_b64 vcc, exec, s[38:39]
	s_cbranch_vccz .LBB0_177
	s_barrier

; #define PG8_STAGE(bufoff, gbase, voff) do { const __amdgpu_buffer_rsrc_t _rs = __builtin_amdgcn_make_buffer_rsrc((void*)(gbase), 0, 0x7fffffff, 0x00020000); _Pragma("unroll") for (int _i = 0; _i < 2; ++_i) \
;         __builtin_amdgcn_raw_ptr_buffer_load_lds(_rs, (LAS unsigned*)(lds + (bufoff) + ldsw + _i * 8192), 16, (int)(voff)[_i], 0, 0, 0); } while (0)
; #define PG8_WAIT_V(n) asm volatile("s_waitcnt vmcnt(" #n ")" ::: "memory")
; #define PG8_WAIT_L(n) asm volatile("s_waitcnt lgkmcnt(" #n ")" ::: "memory")
; #define PG8_BAR __builtin_amdgcn_s_barrier()
; #define PG8_SCHED __builtin_amdgcn_sched_barrier(0)
; template <class Epi, class Sched, bool F8 = false>
; __device__ __forceinline__ void gemm_phase(LAS unsigned char* lds, const int lda, const int ldb, const Sched& S, const Epi& E) {
;     ...
;             const char* a1 = cA + (size_t)(t + 1) * kstep;
;             const char* a2 = last ? nA : cA + (size_t)(t + 2) * kstep; const char* b2 = last ? nB : cB + (size_t)(t + 2) * kstepB;
;             const char* a3 = a2 + kstep; const char* b3 = b2 + kstepB;
;     ...
;             PG8_LDB(B0, 0, 0); PG8_LDB(B1, 0, 1); PG8_SCHED; PG8_LDA(At, 0, 0); PG8_STAGE(PG8_SA(1, 1), a1 + hstepA, voffA);
;             PG8_WAIT_V(8); PG8_WAIT_L(0); PG8_BAR; PG8_MMA(0, 0, At, B0); PG8_MMA(0, 1, At, B1); PG8_BAR; PG8_SCHED;
;             PG8_LDA(At, 0, 1); PG8_STAGE(PG8_SB(0, 0), b2, voffB); PG8_STAGE(PG8_SB(0, 1), b2 + hstepB, voffB); PG8_STAGE(PG8_SA(0, 0), a2, voffA);
;             PG8_WAIT_V(8); PG8_WAIT_L(0); PG8_BAR; PG8_MMA(1, 0, At, B0); PG8_MMA(1, 1, At, B1); PG8_BAR; PG8_SCHED;
.LBB0_408:
	ds_read_b128 v[104:107], v180
	ds_read_b128 v[108:111], v180 offset:1024
	ds_read_b128 v[136:139], v180 offset:2048
	ds_read_b128 v[140:143], v180 offset:3072
	ds_read_b128 v[148:151], v181
	ds_read_b128 v[152:155], v181 offset:1024
	ds_read_b128 v[156:159], v181 offset:2048
	ds_read_b128 v[160:163], v181 offset:3072
	s_add_i32 s64, s4, 2
	s_add_u32 s5, vcc_hi, 0xfff80080
	s_addc_u32 s16, s35, -1
	s_cmp_eq_u32 s62, s4
	s_cselect_b32 s40, s70, s5
	s_cselect_b32 s19, s71, s16
	s_cselect_b32 s18, s73, vcc_lo
	s_cselect_b32 s36, s72, s63
	s_add_u32 s16, s40, 0x80
	s_addc_u32 s17, s19, 0
	s_and_b32 s5, s35, 0xffff
	s_mov_b32 s4, vcc_hi
	s_mov_b32 m0, s92
	ds_read_b128 v[164:167], v182
	ds_read_b128 v[168:171], v182 offset:1024
	ds_read_b128 v[172:175], v182 offset:2048
	ds_read_b128 v[186:189], v182 offset:3072
	ds_read_b128 v[190:193], v182 offset:4096
	ds_read_b128 v[194:197], v182 offset:5120
	ds_read_b128 v[198:201], v182 offset:6144
	ds_read_b128 v[202:205], v182 offset:7168
	buffer_load_dwordx4 v176, s[4:7], 0 offen lds
	s_mov_b32 m0, s93
	s_nop 0
	buffer_load_dwordx4 v178, s[4:7], 0 offen lds
	s_nop 0
	s_waitcnt vmcnt(8)
	s_waitcnt lgkmcnt(0)
	s_barrier
	s_setprio 1
	v_mfma_f32_16x16x32_bf16 v[132:135], v[104:107], v[164:167], v[132:135]
	v_mfma_f32_16x16x32_bf16 v[128:131], v[136:139], v[164:167], v[128:131]
	v_mfma_f32_16x16x32_bf16 v[124:127], v[104:107], v[172:175], v[124:127]
	v_mfma_f32_16x16x32_bf16 v[120:123], v[136:139], v[172:175], v[120:123]
	v_mfma_f32_16x16x32_bf16 v[116:119], v[104:107], v[190:193], v[116:119]
	v_mfma_f32_16x16x32_bf16 v[112:115], v[136:139], v[190:193], v[112:115]
	v_mfma_f32_16x16x32_bf16 v[100:103], v[104:107], v[198:201], v[100:103]
	v_mfma_f32_16x16x32_bf16 v[96:99], v[136:139], v[198:201], v[96:99]
	v_mfma_f32_16x16x32_bf16 v[132:135], v[108:111], v[168:171], v[132:135]
	v_mfma_f32_16x16x32_bf16 v[128:131], v[140:143], v[168:171], v[128:131]
	v_mfma_f32_16x16x32_bf16 v[124:127], v[108:111], v[186:189], v[124:127]
	v_mfma_f32_16x16x32_bf16 v[120:123], v[140:143], v[186:189], v[120:123]
	v_mfma_f32_16x16x32_bf16 v[116:119], v[108:111], v[194:197], v[116:119]
	v_mfma_f32_16x16x32_bf16 v[112:115], v[140:143], v[194:197], v[112:115]
	v_mfma_f32_16x16x32_bf16 v[100:103], v[108:111], v[202:205], v[100:103]
	v_mfma_f32_16x16x32_bf16 v[96:99], v[140:143], v[202:205], v[96:99]
	s_setprio 0
	s_setprio 1
	v_mfma_f32_16x16x32_bf16 v[60:63], v[148:151], v[164:167], v[60:63]
	v_mfma_f32_16x16x32_bf16 v[56:59], v[156:159], v[164:167], v[56:59]
	v_mfma_f32_16x16x32_bf16 v[52:55], v[148:151], v[172:175], v[52:55]
	v_mfma_f32_16x16x32_bf16 v[48:51], v[156:159], v[172:175], v[48:51]
	v_mfma_f32_16x16x32_bf16 v[44:47], v[148:151], v[190:193], v[44:47]
	v_mfma_f32_16x16x32_bf16 v[40:43], v[156:159], v[190:193], v[40:43]
	v_mfma_f32_16x16x32_bf16 v[36:39], v[148:151], v[198:201], v[36:39]
	v_mfma_f32_16x16x32_bf16 v[32:35], v[156:159], v[198:201], v[32:35]
	v_mfma_f32_16x16x32_bf16 v[60:63], v[152:155], v[168:171], v[60:63]
	v_mfma_f32_16x16x32_bf16 v[56:59], v[160:163], v[168:171], v[56:59]
	v_mfma_f32_16x16x32_bf16 v[52:55], v[152:155], v[186:189], v[52:55]
	v_mfma_f32_16x16x32_bf16 v[48:51], v[160:163], v[186:189], v[48:51]
	v_mfma_f32_16x16x32_bf16 v[44:47], v[152:155], v[194:197], v[44:47]
	v_mfma_f32_16x16x32_bf16 v[40:43], v[160:163], v[194:197], v[40:43]
	v_mfma_f32_16x16x32_bf16 v[36:39], v[152:155], v[202:205], v[36:39]
	v_mfma_f32_16x16x32_bf16 v[32:35], v[160:163], v[202:205], v[32:35]
	s_setprio 0
	s_barrier
	s_and_b32 s37, s18, 0xffff
	s_mov_b32 m0, s75
	s_mov_b32 s38, s6
	s_mov_b32 s39, s7
	s_add_u32 s4, s36, 0x4000
	ds_read_b128 v[164:167], v182 offset:16384
	ds_read_b128 v[168:171], v182 offset:17408
	ds_read_b128 v[172:175], v182 offset:18432
	ds_read_b128 v[186:189], v182 offset:19456
	ds_read_b128 v[190:193], v182 offset:20480
	ds_read_b128 v[194:197], v182 offset:21504
	ds_read_b128 v[198:201], v182 offset:22528
	ds_read_b128 v[202:205], v182 offset:23552
	buffer_load_dwordx4 v177, s[36:39], 0 offen lds
	s_mov_b32 m0, s77
	s_addc_u32 s5, s18, 0
	buffer_load_dwordx4 v179, s[36:39], 0 offen lds
	s_and_b32 s5, s5, 0xffff
	s_mov_b32 m0, s78
	s_and_b32 s41, s19, 0xffff
	buffer_load_dwordx4 v177, s[4:7], 0 offen lds
	s_mov_b32 m0, s79
	s_mov_b32 s42, s6
	buffer_load_dwordx4 v179, s[4:7], 0 offen lds
	s_mov_b32 s43, s7
	s_mov_b32 m0, s74
	s_nop 0
	buffer_load_dwordx4 v176, s[40:43], 0 offen lds
	s_mov_b32 m0, s80
	s_nop 0
	buffer_load_dwordx4 v178, s[40:43], 0 offen lds
	s_nop 0
	s_waitcnt vmcnt(8)
	s_waitcnt lgkmcnt(0)
	s_barrier
; #define PG8_STAGE(bufoff, gbase, voff) do { const __amdgpu_buffer_rsrc_t _rs = __builtin_amdgcn_make_buffer_rsrc((void*)(gbase), 0, 0x7fffffff, 0x00020000); _Pragma("unroll") for (int _i = 0; _i < 2; ++_i) \
;         __builtin_amdgcn_raw_ptr_buffer_load_lds(_rs, (LAS unsigned*)(lds + (bufoff) + ldsw + _i * 8192), 16, (int)(voff)[_i], 0, 0, 0); } while (0)
; #define PG8_WAIT_V(n) asm volatile("s_waitcnt vmcnt(" #n ")" ::: "memory")
; #define PG8_WAIT_L(n) asm volatile("s_waitcnt lgkmcnt(" #n ")" ::: "memory")
; #define PG8_BAR __builtin_amdgcn_s_barrier()
; #define PG8_SCHED __builtin_amdgcn_sched_barrier(0)
; template <class Epi, class Sched, bool F8 = false>
; __device__ __forceinline__ void gemm_phase(LAS unsigned char* lds, const int lda, const int ldb, const Sched& S, const Epi& E) {
;     ...
;             PG8_WAIT_V(8); PG8_WAIT_L(0); PG8_BAR; PG8_MMA(1, 0, At, B0); PG8_MMA(1, 1, At, B1); PG8_BAR; PG8_SCHED;
;             PG8_LDB(B0, 1, 0); PG8_LDB(B1, 1, 1); PG8_SCHED; PG8_LDA(At, 1, 0); PG8_STAGE(PG8_SA(0, 1), a2 + hstepA, voffA);
;             PG8_WAIT_V(8); PG8_WAIT_L(0); PG8_BAR; PG8_MMA(0, 0, At, B0); PG8_MMA(0, 1, At, B1); PG8_BAR; PG8_SCHED;
	s_setprio 1
	v_mfma_f32_16x16x32_bf16 v[92:95], v[104:107], v[164:167], v[92:95]
	v_mfma_f32_16x16x32_bf16 v[88:91], v[136:139], v[164:167], v[88:91]
	v_mfma_f32_16x16x32_bf16 v[84:87], v[104:107], v[172:175], v[84:87]
	v_mfma_f32_16x16x32_bf16 v[80:83], v[136:139], v[172:175], v[80:83]
	v_mfma_f32_16x16x32_bf16 v[76:79], v[104:107], v[190:193], v[76:79]
	v_mfma_f32_16x16x32_bf16 v[72:75], v[136:139], v[190:193], v[72:75]
	v_mfma_f32_16x16x32_bf16 v[68:71], v[104:107], v[198:201], v[68:71]
	v_mfma_f32_16x16x32_bf16 v[64:67], v[136:139], v[198:201], v[64:67]
	v_mfma_f32_16x16x32_bf16 v[92:95], v[108:111], v[168:171], v[92:95]
	v_mfma_f32_16x16x32_bf16 v[88:91], v[140:143], v[168:171], v[88:91]
	v_mfma_f32_16x16x32_bf16 v[84:87], v[108:111], v[186:189], v[84:87]
	v_mfma_f32_16x16x32_bf16 v[80:83], v[140:143], v[186:189], v[80:83]
	v_mfma_f32_16x16x32_bf16 v[76:79], v[108:111], v[194:197], v[76:79]
	v_mfma_f32_16x16x32_bf16 v[72:75], v[140:143], v[194:197], v[72:75]
	v_mfma_f32_16x16x32_bf16 v[68:71], v[108:111], v[202:205], v[68:71]
	v_mfma_f32_16x16x32_bf16 v[64:67], v[140:143], v[202:205], v[64:67]
	s_setprio 0
	s_setprio 1
	v_mfma_f32_16x16x32_bf16 v[28:31], v[148:151], v[164:167], v[28:31]
	v_mfma_f32_16x16x32_bf16 v[24:27], v[156:159], v[164:167], v[24:27]
	v_mfma_f32_16x16x32_bf16 v[20:23], v[148:151], v[172:175], v[20:23]
	v_mfma_f32_16x16x32_bf16 v[16:19], v[156:159], v[172:175], v[16:19]
	v_mfma_f32_16x16x32_bf16 v[12:15], v[148:151], v[190:193], v[12:15]
	v_mfma_f32_16x16x32_bf16 v[8:11], v[156:159], v[190:193], v[8:11]
	v_mfma_f32_16x16x32_bf16 v[4:7], v[148:151], v[198:201], v[4:7]
	v_mfma_f32_16x16x32_bf16 v[0:3], v[156:159], v[198:201], v[0:3]
	v_mfma_f32_16x16x32_bf16 v[28:31], v[152:155], v[168:171], v[28:31]
	v_mfma_f32_16x16x32_bf16 v[24:27], v[160:163], v[168:171], v[24:27]
	v_mfma_f32_16x16x32_bf16 v[20:23], v[152:155], v[186:189], v[20:23]
	v_mfma_f32_16x16x32_bf16 v[16:19], v[160:163], v[186:189], v[16:19]
	v_mfma_f32_16x16x32_bf16 v[12:15], v[152:155], v[194:197], v[12:15]
	v_mfma_f32_16x16x32_bf16 v[8:11], v[160:163], v[194:197], v[8:11]
	v_mfma_f32_16x16x32_bf16 v[4:7], v[152:155], v[202:205], v[4:7]
	v_mfma_f32_16x16x32_bf16 v[0:3], v[160:163], v[202:205], v[0:3]
	s_setprio 0
	s_barrier
	ds_read_b128 v[104:107], v183
	ds_read_b128 v[108:111], v183 offset:1024
	ds_read_b128 v[136:139], v183 offset:2048
	ds_read_b128 v[140:143], v183 offset:3072
	ds_read_b128 v[148:151], v184
	ds_read_b128 v[152:155], v184 offset:1024
	ds_read_b128 v[156:159], v184 offset:2048
	ds_read_b128 v[160:163], v184 offset:3072
	s_add_u32 s4, s40, 0x80000
	s_addc_u32 s5, s19, 0
	s_and_b32 s5, s5, 0xffff
	s_mov_b32 m0, s81
	ds_read_b128 v[164:167], v182 offset:32768
	ds_read_b128 v[168:171], v182 offset:33792
	ds_read_b128 v[172:175], v182 offset:34816
	ds_read_b128 v[186:189], v182 offset:35840
	ds_read_b128 v[190:193], v182 offset:36864
	ds_read_b128 v[194:197], v182 offset:37888
	ds_read_b128 v[198:201], v182 offset:38912
	ds_read_b128 v[202:205], v182 offset:39936
	buffer_load_dwordx4 v176, s[4:7], 0 offen lds
	s_mov_b32 m0, s82
	s_nop 0
	buffer_load_dwordx4 v178, s[4:7], 0 offen lds
	s_waitcnt vmcnt(8)
	s_waitcnt lgkmcnt(0)
	s_barrier
	s_setprio 1
	v_mfma_f32_16x16x32_bf16 v[132:135], v[104:107], v[164:167], v[132:135]
	v_mfma_f32_16x16x32_bf16 v[128:131], v[136:139], v[164:167], v[128:131]
	v_mfma_f32_16x16x32_bf16 v[124:127], v[104:107], v[172:175], v[124:127]
	v_mfma_f32_16x16x32_bf16 v[120:123], v[136:139], v[172:175], v[120:123]
	v_mfma_f32_16x16x32_bf16 v[116:119], v[104:107], v[190:193], v[116:119]
	v_mfma_f32_16x16x32_bf16 v[112:115], v[136:139], v[190:193], v[112:115]
	v_mfma_f32_16x16x32_bf16 v[100:103], v[104:107], v[198:201], v[100:103]
	v_mfma_f32_16x16x32_bf16 v[96:99], v[136:139], v[198:201], v[96:99]
	v_mfma_f32_16x16x32_bf16 v[132:135], v[108:111], v[168:171], v[132:135]
	v_mfma_f32_16x16x32_bf16 v[128:131], v[140:143], v[168:171], v[128:131]
	v_mfma_f32_16x16x32_bf16 v[124:127], v[108:111], v[186:189], v[124:127]
	v_mfma_f32_16x16x32_bf16 v[120:123], v[140:143], v[186:189], v[120:123]
	v_mfma_f32_16x16x32_bf16 v[116:119], v[108:111], v[194:197], v[116:119]
	v_mfma_f32_16x16x32_bf16 v[112:115], v[140:143], v[194:197], v[112:115]
	v_mfma_f32_16x16x32_bf16 v[100:103], v[108:111], v[202:205], v[100:103]
	v_mfma_f32_16x16x32_bf16 v[96:99], v[140:143], v[202:205], v[96:99]
	s_setprio 0
	s_setprio 1
	v_mfma_f32_16x16x32_bf16 v[60:63], v[148:151], v[164:167], v[60:63]
	v_mfma_f32_16x16x32_bf16 v[56:59], v[156:159], v[164:167], v[56:59]
	v_mfma_f32_16x16x32_bf16 v[52:55], v[148:151], v[172:175], v[52:55]
	v_mfma_f32_16x16x32_bf16 v[48:51], v[156:159], v[172:175], v[48:51]
	v_mfma_f32_16x16x32_bf16 v[44:47], v[148:151], v[190:193], v[44:47]
	v_mfma_f32_16x16x32_bf16 v[40:43], v[156:159], v[190:193], v[40:43]
	v_mfma_f32_16x16x32_bf16 v[36:39], v[148:151], v[198:201], v[36:39]
	v_mfma_f32_16x16x32_bf16 v[32:35], v[156:159], v[198:201], v[32:35]
	v_mfma_f32_16x16x32_bf16 v[60:63], v[152:155], v[168:171], v[60:63]
	v_mfma_f32_16x16x32_bf16 v[56:59], v[160:163], v[168:171], v[56:59]
	v_mfma_f32_16x16x32_bf16 v[52:55], v[152:155], v[186:189], v[52:55]
	v_mfma_f32_16x16x32_bf16 v[48:51], v[160:163], v[186:189], v[48:51]
	v_mfma_f32_16x16x32_bf16 v[44:47], v[152:155], v[194:197], v[44:47]
	v_mfma_f32_16x16x32_bf16 v[40:43], v[160:163], v[194:197], v[40:43]
	v_mfma_f32_16x16x32_bf16 v[36:39], v[152:155], v[202:205], v[36:39]
	v_mfma_f32_16x16x32_bf16 v[32:35], v[160:163], v[202:205], v[32:35]
	s_setprio 0
	s_barrier
; #define PG8_STAGE(bufoff, gbase, voff) do { const __amdgpu_buffer_rsrc_t _rs = __builtin_amdgcn_make_buffer_rsrc((void*)(gbase), 0, 0x7fffffff, 0x00020000); _Pragma("unroll") for (int _i = 0; _i < 2; ++_i) \
;         __builtin_amdgcn_raw_ptr_buffer_load_lds(_rs, (LAS unsigned*)(lds + (bufoff) + ldsw + _i * 8192), 16, (int)(voff)[_i], 0, 0, 0); } while (0)
; #define PG8_WAIT_V(n) asm volatile("s_waitcnt vmcnt(" #n ")" ::: "memory")
; #define PG8_WAIT_L(n) asm volatile("s_waitcnt lgkmcnt(" #n ")" ::: "memory")
; #define PG8_BAR __builtin_amdgcn_s_barrier()
; #define PG8_SCHED __builtin_amdgcn_sched_barrier(0)
; template <class Epi, class Sched, bool F8 = false>
; __device__ __forceinline__ void gemm_phase(LAS unsigned char* lds, const int lda, const int ldb, const Sched& S, const Epi& E) {
;     ...
;             PG8_LDA(At, 1, 1); PG8_STAGE(PG8_SB(1, 0), b3, voffB); PG8_STAGE(PG8_SB(1, 1), b3 + hstepB, voffB); PG8_STAGE(PG8_SA(1, 0), a3, voffA);
;             PG8_WAIT_V(8); PG8_WAIT_L(0); PG8_BAR; PG8_MMA(1, 0, At, B0); PG8_MMA(1, 1, At, B1); PG8_BAR; PG8_SCHED;
;     ...
;         }
;         if (wr == 0) PG8_BAR;
	s_add_u32 s4, s36, 0x8000
	s_addc_u32 s5, s18, 0
	s_mov_b32 m0, s86
	s_and_b32 s5, s5, 0xffff
	ds_read_b128 v[164:167], v182 offset:49152
	ds_read_b128 v[168:171], v182 offset:50176
	ds_read_b128 v[172:175], v182 offset:51200
	ds_read_b128 v[186:189], v182 offset:52224
	ds_read_b128 v[190:193], v182 offset:53248
	ds_read_b128 v[194:197], v182 offset:54272
	ds_read_b128 v[198:201], v182 offset:55296
	ds_read_b128 v[202:205], v182 offset:56320
	buffer_load_dwordx4 v177, s[4:7], 0 offen lds
	s_mov_b32 m0, s87
	s_mov_b32 s19, s7
	buffer_load_dwordx4 v179, s[4:7], 0 offen lds
	s_add_u32 s4, s36, 0xc000
	s_addc_u32 s5, s18, 0
	s_and_b32 s5, s5, 0xffff
	s_mov_b32 m0, s90
	s_and_b32 s17, s17, 0xffff
	buffer_load_dwordx4 v177, s[4:7], 0 offen lds
	s_mov_b32 m0, s91
	s_mov_b32 s18, s6
	buffer_load_dwordx4 v179, s[4:7], 0 offen lds
	s_mov_b32 m0, s88
	s_nop 0
	buffer_load_dwordx4 v176, s[16:19], 0 offen lds
	s_mov_b32 m0, s89
	s_nop 0
	buffer_load_dwordx4 v178, s[16:19], 0 offen lds
	s_waitcnt vmcnt(8)
	s_waitcnt lgkmcnt(0)
	s_barrier
	s_setprio 1
	v_mfma_f32_16x16x32_bf16 v[92:95], v[104:107], v[164:167], v[92:95]
	v_mfma_f32_16x16x32_bf16 v[88:91], v[136:139], v[164:167], v[88:91]
	v_mfma_f32_16x16x32_bf16 v[84:87], v[104:107], v[172:175], v[84:87]
	v_mfma_f32_16x16x32_bf16 v[80:83], v[136:139], v[172:175], v[80:83]
	v_mfma_f32_16x16x32_bf16 v[76:79], v[104:107], v[190:193], v[76:79]
	v_mfma_f32_16x16x32_bf16 v[72:75], v[136:139], v[190:193], v[72:75]
	v_mfma_f32_16x16x32_bf16 v[68:71], v[104:107], v[198:201], v[68:71]
	v_mfma_f32_16x16x32_bf16 v[64:67], v[136:139], v[198:201], v[64:67]
	v_mfma_f32_16x16x32_bf16 v[92:95], v[108:111], v[168:171], v[92:95]
	v_mfma_f32_16x16x32_bf16 v[88:91], v[140:143], v[168:171], v[88:91]
	v_mfma_f32_16x16x32_bf16 v[84:87], v[108:111], v[186:189], v[84:87]
	v_mfma_f32_16x16x32_bf16 v[80:83], v[140:143], v[186:189], v[80:83]
	v_mfma_f32_16x16x32_bf16 v[76:79], v[108:111], v[194:197], v[76:79]
	v_mfma_f32_16x16x32_bf16 v[72:75], v[140:143], v[194:197], v[72:75]
	v_mfma_f32_16x16x32_bf16 v[68:71], v[108:111], v[202:205], v[68:71]
	v_mfma_f32_16x16x32_bf16 v[64:67], v[140:143], v[202:205], v[64:67]
	s_setprio 0
	s_setprio 1
	v_mfma_f32_16x16x32_bf16 v[28:31], v[148:151], v[164:167], v[28:31]
	v_mfma_f32_16x16x32_bf16 v[24:27], v[156:159], v[164:167], v[24:27]
	v_mfma_f32_16x16x32_bf16 v[20:23], v[148:151], v[172:175], v[20:23]
	v_mfma_f32_16x16x32_bf16 v[16:19], v[156:159], v[172:175], v[16:19]
	v_mfma_f32_16x16x32_bf16 v[12:15], v[148:151], v[190:193], v[12:15]
	v_mfma_f32_16x16x32_bf16 v[8:11], v[156:159], v[190:193], v[8:11]
	v_mfma_f32_16x16x32_bf16 v[4:7], v[148:151], v[198:201], v[4:7]
	v_mfma_f32_16x16x32_bf16 v[0:3], v[156:159], v[198:201], v[0:3]
	v_mfma_f32_16x16x32_bf16 v[28:31], v[152:155], v[168:171], v[28:31]
	v_mfma_f32_16x16x32_bf16 v[24:27], v[160:163], v[168:171], v[24:27]
	v_mfma_f32_16x16x32_bf16 v[20:23], v[152:155], v[186:189], v[20:23]
	v_mfma_f32_16x16x32_bf16 v[16:19], v[160:163], v[186:189], v[16:19]
	v_mfma_f32_16x16x32_bf16 v[12:15], v[152:155], v[194:197], v[12:15]
	v_mfma_f32_16x16x32_bf16 v[8:11], v[160:163], v[194:197], v[8:11]
	v_mfma_f32_16x16x32_bf16 v[4:7], v[152:155], v[202:205], v[4:7]
	v_mfma_f32_16x16x32_bf16 v[0:3], v[160:163], v[202:205], v[0:3]
	s_setprio 0
	s_barrier
	s_add_u32 s63, s63, 0x10000
	s_addc_u32 vcc_lo, vcc_lo, 0
	s_add_u32 vcc_hi, vcc_hi, 0x100
	s_addc_u32 s35, s35, 0
	s_cmp_ge_i32 s64, s9
	s_mov_b32 s4, s64
	s_cbranch_scc0 .LBB0_408
	s_and_b64 vcc, exec, s[66:67]
	s_cbranch_vccz .LBB0_411
	s_barrier

; #define PG8_STAGE(bufoff, gbase, voff) do { const __amdgpu_buffer_rsrc_t _rs = __builtin_amdgcn_make_buffer_rsrc((void*)(gbase), 0, 0x7fffffff, 0x00020000); _Pragma("unroll") for (int _i = 0; _i < 2; ++_i) \
;         __builtin_amdgcn_raw_ptr_buffer_load_lds(_rs, (LAS unsigned*)(lds + (bufoff) + ldsw + _i * 8192), 16, (int)(voff)[_i], 0, 0, 0); } while (0)
; #define PG8_WAIT_V(n) asm volatile("s_waitcnt vmcnt(" #n ")" ::: "memory")
; #define PG8_WAIT_L(n) asm volatile("s_waitcnt lgkmcnt(" #n ")" ::: "memory")
; #define PG8_BAR __builtin_amdgcn_s_barrier()
; #define PG8_SCHED __builtin_amdgcn_sched_barrier(0)
; template <class Epi, class Sched, bool F8 = false>
; __device__ __forceinline__ void gemm_phase(LAS unsigned char* lds, const int lda, const int ldb, const Sched& S, const Epi& E) {
;     ...
;             const char* a1 = cA + (size_t)(t + 1) * kstep;
;             const char* a2 = last ? nA : cA + (size_t)(t + 2) * kstep; const char* b2 = last ? nB : cB + (size_t)(t + 2) * kstepB;
;             const char* a3 = a2 + kstep; const char* b3 = b2 + kstepB;
;     ...
;             PG8_LDB(B0, 0, 0); PG8_LDB(B1, 0, 1); PG8_SCHED; PG8_LDA(At, 0, 0); PG8_STAGE(PG8_SA(1, 1), a1 + hstepA, voffA);
;             PG8_WAIT_V(8); PG8_WAIT_L(0); PG8_BAR; PG8_MMA(0, 0, At, B0); PG8_MMA(0, 1, At, B1); PG8_BAR; PG8_SCHED;
;             PG8_LDA(At, 0, 1); PG8_STAGE(PG8_SB(0, 0), b2, voffB); PG8_STAGE(PG8_SB(0, 1), b2 + hstepB, voffB); PG8_STAGE(PG8_SA(0, 0), a2, voffA);
;             PG8_WAIT_V(8); PG8_WAIT_L(0); PG8_BAR; PG8_MMA(1, 0, At, B0); PG8_MMA(1, 1, At, B1); PG8_BAR; PG8_SCHED;
.LBB0_485:
	v_add_u32_e32 v144, 0x10000, v152
	v_add_u32_e32 v166, 0x14000, v152
	ds_read_b128 v[132:135], v144
	ds_read_b128 v[136:139], v144 offset:1024
	ds_read_b128 v[140:143], v144 offset:2048
	ds_read_b128 v[144:147], v144 offset:3072
	ds_read_b128 v[154:157], v166
	ds_read_b128 v[158:161], v166 offset:1024
	ds_read_b128 v[162:165], v166 offset:2048
	ds_read_b128 v[166:169], v166 offset:3072
	s_add_u32 s4, s47, 0xfff80080
	s_addc_u32 s5, s62, -1
	s_cmp_eq_u32 s63, 28
	s_cselect_b32 s40, s48, s4
	s_cselect_b32 s19, s49, s5
	s_cselect_b32 s18, s51, s33
	s_cselect_b32 s36, s50, s9
	s_add_u32 s16, s40, 0x80
	s_addc_u32 s17, s19, 0
	s_and_b32 s5, s62, 0xffff
	s_mov_b32 s4, s47
	s_mov_b32 m0, s91
	ds_read_b128 v[170:173], v153
	ds_read_b128 v[174:177], v153 offset:1024
	ds_read_b128 v[178:181], v153 offset:2048
	ds_read_b128 v[182:185], v153 offset:3072
	ds_read_b128 v[186:189], v153 offset:4096
	ds_read_b128 v[190:193], v153 offset:5120
	ds_read_b128 v[194:197], v153 offset:6144
	ds_read_b128 v[198:201], v153 offset:7168
	buffer_load_dwordx4 v148, s[4:7], 0 offen lds
	s_mov_b32 m0, s92
	s_nop 0
	buffer_load_dwordx4 v150, s[4:7], 0 offen lds
	s_nop 0
	s_waitcnt vmcnt(8)
	s_waitcnt lgkmcnt(0)
	s_barrier
	s_setprio 1
	v_mfma_f32_16x16x32_bf16 v[124:127], v[132:135], v[170:173], v[124:127]
	v_mfma_f32_16x16x32_bf16 v[120:123], v[140:143], v[170:173], v[120:123]
	v_mfma_f32_16x16x32_bf16 v[116:119], v[132:135], v[178:181], v[116:119]
	v_mfma_f32_16x16x32_bf16 v[112:115], v[140:143], v[178:181], v[112:115]
	v_mfma_f32_16x16x32_bf16 v[108:111], v[132:135], v[186:189], v[108:111]
	v_mfma_f32_16x16x32_bf16 v[104:107], v[140:143], v[186:189], v[104:107]
	v_mfma_f32_16x16x32_bf16 v[100:103], v[132:135], v[194:197], v[100:103]
	v_mfma_f32_16x16x32_bf16 v[96:99], v[140:143], v[194:197], v[96:99]
	v_mfma_f32_16x16x32_bf16 v[124:127], v[136:139], v[174:177], v[124:127]
	v_mfma_f32_16x16x32_bf16 v[120:123], v[144:147], v[174:177], v[120:123]
	v_mfma_f32_16x16x32_bf16 v[116:119], v[136:139], v[182:185], v[116:119]
	v_mfma_f32_16x16x32_bf16 v[112:115], v[144:147], v[182:185], v[112:115]
	v_mfma_f32_16x16x32_bf16 v[108:111], v[136:139], v[190:193], v[108:111]
	v_mfma_f32_16x16x32_bf16 v[104:107], v[144:147], v[190:193], v[104:107]
	v_mfma_f32_16x16x32_bf16 v[100:103], v[136:139], v[198:201], v[100:103]
	v_mfma_f32_16x16x32_bf16 v[96:99], v[144:147], v[198:201], v[96:99]
	s_setprio 0
	s_setprio 1
	v_mfma_f32_16x16x32_bf16 v[92:95], v[154:157], v[170:173], v[92:95]
	v_mfma_f32_16x16x32_bf16 v[88:91], v[162:165], v[170:173], v[88:91]
	v_mfma_f32_16x16x32_bf16 v[84:87], v[154:157], v[178:181], v[84:87]
	v_mfma_f32_16x16x32_bf16 v[80:83], v[162:165], v[178:181], v[80:83]
	v_mfma_f32_16x16x32_bf16 v[76:79], v[154:157], v[186:189], v[76:79]
	v_mfma_f32_16x16x32_bf16 v[72:75], v[162:165], v[186:189], v[72:75]
	v_mfma_f32_16x16x32_bf16 v[68:71], v[154:157], v[194:197], v[68:71]
	v_mfma_f32_16x16x32_bf16 v[64:67], v[162:165], v[194:197], v[64:67]
	v_mfma_f32_16x16x32_bf16 v[92:95], v[158:161], v[174:177], v[92:95]
	v_mfma_f32_16x16x32_bf16 v[88:91], v[166:169], v[174:177], v[88:91]
	v_mfma_f32_16x16x32_bf16 v[84:87], v[158:161], v[182:185], v[84:87]
	v_mfma_f32_16x16x32_bf16 v[80:83], v[166:169], v[182:185], v[80:83]
	v_mfma_f32_16x16x32_bf16 v[76:79], v[158:161], v[190:193], v[76:79]
	v_mfma_f32_16x16x32_bf16 v[72:75], v[166:169], v[190:193], v[72:75]
	v_mfma_f32_16x16x32_bf16 v[68:71], v[158:161], v[198:201], v[68:71]
	v_mfma_f32_16x16x32_bf16 v[64:67], v[166:169], v[198:201], v[64:67]
	s_setprio 0
	s_barrier
	s_and_b32 s37, s18, 0xffff
	s_mov_b32 m0, s70
	s_mov_b32 s38, s6
	s_mov_b32 s39, s7
	s_add_u32 s4, s36, 0x4000
	ds_read_b128 v[170:173], v153 offset:16384
	ds_read_b128 v[174:177], v153 offset:17408
	ds_read_b128 v[178:181], v153 offset:18432
	ds_read_b128 v[182:185], v153 offset:19456
	ds_read_b128 v[186:189], v153 offset:20480
	ds_read_b128 v[190:193], v153 offset:21504
	ds_read_b128 v[194:197], v153 offset:22528
	ds_read_b128 v[198:201], v153 offset:23552
	buffer_load_dwordx4 v149, s[36:39], 0 offen lds
	s_mov_b32 m0, s71
	s_addc_u32 s5, s18, 0
	buffer_load_dwordx4 v151, s[36:39], 0 offen lds
	s_and_b32 s5, s5, 0xffff
	s_mov_b32 m0, s72
	s_and_b32 s41, s19, 0xffff
	buffer_load_dwordx4 v149, s[4:7], 0 offen lds
	s_mov_b32 m0, s73
	s_mov_b32 s42, s6
	buffer_load_dwordx4 v151, s[4:7], 0 offen lds
	s_mov_b32 s43, s7
	s_mov_b32 m0, s67
	s_nop 0
	buffer_load_dwordx4 v148, s[40:43], 0 offen lds
	s_mov_b32 m0, s74
	s_nop 0
	buffer_load_dwordx4 v150, s[40:43], 0 offen lds
	s_nop 0
	s_waitcnt vmcnt(8)
	s_waitcnt lgkmcnt(0)
	s_barrier
; #define PG8_STAGE(bufoff, gbase, voff) do { const __amdgpu_buffer_rsrc_t _rs = __builtin_amdgcn_make_buffer_rsrc((void*)(gbase), 0, 0x7fffffff, 0x00020000); _Pragma("unroll") for (int _i = 0; _i < 2; ++_i) \
;         __builtin_amdgcn_raw_ptr_buffer_load_lds(_rs, (LAS unsigned*)(lds + (bufoff) + ldsw + _i * 8192), 16, (int)(voff)[_i], 0, 0, 0); } while (0)
; #define PG8_WAIT_V(n) asm volatile("s_waitcnt vmcnt(" #n ")" ::: "memory")
; #define PG8_WAIT_L(n) asm volatile("s_waitcnt lgkmcnt(" #n ")" ::: "memory")
; #define PG8_BAR __builtin_amdgcn_s_barrier()
; #define PG8_SCHED __builtin_amdgcn_sched_barrier(0)
; template <class Epi, class Sched, bool F8 = false>
; __device__ __forceinline__ void gemm_phase(LAS unsigned char* lds, const int lda, const int ldb, const Sched& S, const Epi& E) {
;     ...
;             PG8_WAIT_V(8); PG8_WAIT_L(0); PG8_BAR; PG8_MMA(1, 0, At, B0); PG8_MMA(1, 1, At, B1); PG8_BAR; PG8_SCHED;
;             PG8_LDB(B0, 1, 0); PG8_LDB(B1, 1, 1); PG8_SCHED; PG8_LDA(At, 1, 0); PG8_STAGE(PG8_SA(0, 1), a2 + hstepA, voffA);
;             PG8_WAIT_V(8); PG8_WAIT_L(0); PG8_BAR; PG8_MMA(0, 0, At, B0); PG8_MMA(0, 1, At, B1); PG8_BAR; PG8_SCHED;
	s_setprio 1
	v_mfma_f32_16x16x32_bf16 v[60:63], v[132:135], v[170:173], v[60:63]
	v_mfma_f32_16x16x32_bf16 v[56:59], v[140:143], v[170:173], v[56:59]
	v_mfma_f32_16x16x32_bf16 v[52:55], v[132:135], v[178:181], v[52:55]
	v_mfma_f32_16x16x32_bf16 v[48:51], v[140:143], v[178:181], v[48:51]
	v_mfma_f32_16x16x32_bf16 v[44:47], v[132:135], v[186:189], v[44:47]
	v_mfma_f32_16x16x32_bf16 v[40:43], v[140:143], v[186:189], v[40:43]
	v_mfma_f32_16x16x32_bf16 v[36:39], v[132:135], v[194:197], v[36:39]
	v_mfma_f32_16x16x32_bf16 v[32:35], v[140:143], v[194:197], v[32:35]
	v_mfma_f32_16x16x32_bf16 v[60:63], v[136:139], v[174:177], v[60:63]
	v_mfma_f32_16x16x32_bf16 v[56:59], v[144:147], v[174:177], v[56:59]
	v_mfma_f32_16x16x32_bf16 v[52:55], v[136:139], v[182:185], v[52:55]
	v_mfma_f32_16x16x32_bf16 v[48:51], v[144:147], v[182:185], v[48:51]
	v_mfma_f32_16x16x32_bf16 v[44:47], v[136:139], v[190:193], v[44:47]
	v_mfma_f32_16x16x32_bf16 v[40:43], v[144:147], v[190:193], v[40:43]
	v_mfma_f32_16x16x32_bf16 v[36:39], v[136:139], v[198:201], v[36:39]
	v_mfma_f32_16x16x32_bf16 v[32:35], v[144:147], v[198:201], v[32:35]
	s_setprio 0
	s_setprio 1
	v_mfma_f32_16x16x32_bf16 v[28:31], v[154:157], v[170:173], v[28:31]
	v_mfma_f32_16x16x32_bf16 v[24:27], v[162:165], v[170:173], v[24:27]
	v_mfma_f32_16x16x32_bf16 v[20:23], v[154:157], v[178:181], v[20:23]
	v_mfma_f32_16x16x32_bf16 v[16:19], v[162:165], v[178:181], v[16:19]
	v_mfma_f32_16x16x32_bf16 v[12:15], v[154:157], v[186:189], v[12:15]
	v_mfma_f32_16x16x32_bf16 v[8:11], v[162:165], v[186:189], v[8:11]
	v_mfma_f32_16x16x32_bf16 v[4:7], v[154:157], v[194:197], v[4:7]
	v_mfma_f32_16x16x32_bf16 v[0:3], v[162:165], v[194:197], v[0:3]
	v_mfma_f32_16x16x32_bf16 v[28:31], v[158:161], v[174:177], v[28:31]
	v_mfma_f32_16x16x32_bf16 v[24:27], v[166:169], v[174:177], v[24:27]
	v_mfma_f32_16x16x32_bf16 v[20:23], v[158:161], v[182:185], v[20:23]
	v_mfma_f32_16x16x32_bf16 v[16:19], v[166:169], v[182:185], v[16:19]
	v_mfma_f32_16x16x32_bf16 v[12:15], v[158:161], v[190:193], v[12:15]
	v_mfma_f32_16x16x32_bf16 v[8:11], v[166:169], v[190:193], v[8:11]
	v_mfma_f32_16x16x32_bf16 v[4:7], v[158:161], v[198:201], v[4:7]
	v_mfma_f32_16x16x32_bf16 v[0:3], v[166:169], v[198:201], v[0:3]
	s_setprio 0
	s_barrier
	v_add_u32_e32 v144, 0x18000, v152
	v_add_u32_e32 v166, 0x1c000, v152
	ds_read_b128 v[132:135], v144
	ds_read_b128 v[136:139], v144 offset:1024
	ds_read_b128 v[140:143], v144 offset:2048
	ds_read_b128 v[144:147], v144 offset:3072
	ds_read_b128 v[154:157], v166
	ds_read_b128 v[158:161], v166 offset:1024
	ds_read_b128 v[162:165], v166 offset:2048
	ds_read_b128 v[166:169], v166 offset:3072
	s_add_u32 s4, s40, 0x80000
	s_addc_u32 s5, s19, 0
	s_and_b32 s5, s5, 0xffff
	s_mov_b32 m0, s75
	ds_read_b128 v[170:173], v153 offset:32768
	ds_read_b128 v[174:177], v153 offset:33792
	ds_read_b128 v[178:181], v153 offset:34816
	ds_read_b128 v[182:185], v153 offset:35840
	ds_read_b128 v[186:189], v153 offset:36864
	ds_read_b128 v[190:193], v153 offset:37888
	ds_read_b128 v[194:197], v153 offset:38912
	ds_read_b128 v[198:201], v153 offset:39936
	buffer_load_dwordx4 v148, s[4:7], 0 offen lds
	s_mov_b32 m0, s76
	s_nop 0
	buffer_load_dwordx4 v150, s[4:7], 0 offen lds
	s_waitcnt vmcnt(8)
	s_waitcnt lgkmcnt(0)
	s_barrier
	s_setprio 1
	v_mfma_f32_16x16x32_bf16 v[124:127], v[132:135], v[170:173], v[124:127]
	v_mfma_f32_16x16x32_bf16 v[120:123], v[140:143], v[170:173], v[120:123]
	v_mfma_f32_16x16x32_bf16 v[116:119], v[132:135], v[178:181], v[116:119]
	v_mfma_f32_16x16x32_bf16 v[112:115], v[140:143], v[178:181], v[112:115]
	v_mfma_f32_16x16x32_bf16 v[108:111], v[132:135], v[186:189], v[108:111]
	v_mfma_f32_16x16x32_bf16 v[104:107], v[140:143], v[186:189], v[104:107]
	v_mfma_f32_16x16x32_bf16 v[100:103], v[132:135], v[194:197], v[100:103]
	v_mfma_f32_16x16x32_bf16 v[96:99], v[140:143], v[194:197], v[96:99]
	v_mfma_f32_16x16x32_bf16 v[124:127], v[136:139], v[174:177], v[124:127]
	v_mfma_f32_16x16x32_bf16 v[120:123], v[144:147], v[174:177], v[120:123]
	v_mfma_f32_16x16x32_bf16 v[116:119], v[136:139], v[182:185], v[116:119]
	v_mfma_f32_16x16x32_bf16 v[112:115], v[144:147], v[182:185], v[112:115]
	v_mfma_f32_16x16x32_bf16 v[108:111], v[136:139], v[190:193], v[108:111]
	v_mfma_f32_16x16x32_bf16 v[104:107], v[144:147], v[190:193], v[104:107]
	v_mfma_f32_16x16x32_bf16 v[100:103], v[136:139], v[198:201], v[100:103]
	v_mfma_f32_16x16x32_bf16 v[96:99], v[144:147], v[198:201], v[96:99]
	s_setprio 0
	s_setprio 1
	v_mfma_f32_16x16x32_bf16 v[92:95], v[154:157], v[170:173], v[92:95]
	v_mfma_f32_16x16x32_bf16 v[88:91], v[162:165], v[170:173], v[88:91]
	v_mfma_f32_16x16x32_bf16 v[84:87], v[154:157], v[178:181], v[84:87]
	v_mfma_f32_16x16x32_bf16 v[80:83], v[162:165], v[178:181], v[80:83]
	v_mfma_f32_16x16x32_bf16 v[76:79], v[154:157], v[186:189], v[76:79]
	v_mfma_f32_16x16x32_bf16 v[72:75], v[162:165], v[186:189], v[72:75]
	v_mfma_f32_16x16x32_bf16 v[68:71], v[154:157], v[194:197], v[68:71]
	v_mfma_f32_16x16x32_bf16 v[64:67], v[162:165], v[194:197], v[64:67]
	v_mfma_f32_16x16x32_bf16 v[92:95], v[158:161], v[174:177], v[92:95]
	v_mfma_f32_16x16x32_bf16 v[88:91], v[166:169], v[174:177], v[88:91]
	v_mfma_f32_16x16x32_bf16 v[84:87], v[158:161], v[182:185], v[84:87]
	v_mfma_f32_16x16x32_bf16 v[80:83], v[166:169], v[182:185], v[80:83]
	v_mfma_f32_16x16x32_bf16 v[76:79], v[158:161], v[190:193], v[76:79]
	v_mfma_f32_16x16x32_bf16 v[72:75], v[166:169], v[190:193], v[72:75]
	v_mfma_f32_16x16x32_bf16 v[68:71], v[158:161], v[198:201], v[68:71]
	v_mfma_f32_16x16x32_bf16 v[64:67], v[166:169], v[198:201], v[64:67]
	s_setprio 0
	s_barrier
; #define PG8_STAGE(bufoff, gbase, voff) do { const __amdgpu_buffer_rsrc_t _rs = __builtin_amdgcn_make_buffer_rsrc((void*)(gbase), 0, 0x7fffffff, 0x00020000); _Pragma("unroll") for (int _i = 0; _i < 2; ++_i) \
;         __builtin_amdgcn_raw_ptr_buffer_load_lds(_rs, (LAS unsigned*)(lds + (bufoff) + ldsw + _i * 8192), 16, (int)(voff)[_i], 0, 0, 0); } while (0)
; #define PG8_WAIT_V(n) asm volatile("s_waitcnt vmcnt(" #n ")" ::: "memory")
; #define PG8_WAIT_L(n) asm volatile("s_waitcnt lgkmcnt(" #n ")" ::: "memory")
; #define PG8_BAR __builtin_amdgcn_s_barrier()
; #define PG8_SCHED __builtin_amdgcn_sched_barrier(0)
; template <class Epi, class Sched, bool F8 = false>
; __device__ __forceinline__ void gemm_phase(LAS unsigned char* lds, const int lda, const int ldb, const Sched& S, const Epi& E) {
;     ...
;             PG8_LDA(At, 1, 1); PG8_STAGE(PG8_SB(1, 0), b3, voffB); PG8_STAGE(PG8_SB(1, 1), b3 + hstepB, voffB); PG8_STAGE(PG8_SA(1, 0), a3, voffA);
;             PG8_WAIT_V(8); PG8_WAIT_L(0); PG8_BAR; PG8_MMA(1, 0, At, B0); PG8_MMA(1, 1, At, B1); PG8_BAR; PG8_SCHED;
;     ...
;         }
;         if (wr == 0) PG8_BAR;
	s_add_u32 s4, s36, 0x8000
	s_addc_u32 s5, s18, 0
	s_mov_b32 m0, s85
	s_and_b32 s5, s5, 0xffff
	ds_read_b128 v[170:173], v153 offset:49152
	ds_read_b128 v[174:177], v153 offset:50176
	ds_read_b128 v[178:181], v153 offset:51200
	ds_read_b128 v[182:185], v153 offset:52224
	ds_read_b128 v[186:189], v153 offset:53248
	ds_read_b128 v[190:193], v153 offset:54272
	ds_read_b128 v[194:197], v153 offset:55296
	ds_read_b128 v[198:201], v153 offset:56320
	buffer_load_dwordx4 v149, s[4:7], 0 offen lds
	s_mov_b32 m0, s86
	s_mov_b32 s19, s7
	buffer_load_dwordx4 v151, s[4:7], 0 offen lds
	s_add_u32 s4, s36, 0xc000
	s_addc_u32 s5, s18, 0
	s_and_b32 s5, s5, 0xffff
	s_mov_b32 m0, s89
	s_and_b32 s17, s17, 0xffff
	buffer_load_dwordx4 v149, s[4:7], 0 offen lds
	s_mov_b32 m0, s90
	s_mov_b32 s18, s6
	buffer_load_dwordx4 v151, s[4:7], 0 offen lds
	s_mov_b32 m0, s87
	s_nop 0
	buffer_load_dwordx4 v148, s[16:19], 0 offen lds
	s_mov_b32 m0, s88
	s_nop 0
	buffer_load_dwordx4 v150, s[16:19], 0 offen lds
	s_waitcnt vmcnt(8)
	s_waitcnt lgkmcnt(0)
	s_barrier
	s_setprio 1
	v_mfma_f32_16x16x32_bf16 v[60:63], v[132:135], v[170:173], v[60:63]
	v_mfma_f32_16x16x32_bf16 v[56:59], v[140:143], v[170:173], v[56:59]
	v_mfma_f32_16x16x32_bf16 v[52:55], v[132:135], v[178:181], v[52:55]
	v_mfma_f32_16x16x32_bf16 v[48:51], v[140:143], v[178:181], v[48:51]
	v_mfma_f32_16x16x32_bf16 v[44:47], v[132:135], v[186:189], v[44:47]
	v_mfma_f32_16x16x32_bf16 v[40:43], v[140:143], v[186:189], v[40:43]
	v_mfma_f32_16x16x32_bf16 v[36:39], v[132:135], v[194:197], v[36:39]
	v_mfma_f32_16x16x32_bf16 v[32:35], v[140:143], v[194:197], v[32:35]
	v_mfma_f32_16x16x32_bf16 v[60:63], v[136:139], v[174:177], v[60:63]
	v_mfma_f32_16x16x32_bf16 v[56:59], v[144:147], v[174:177], v[56:59]
	v_mfma_f32_16x16x32_bf16 v[52:55], v[136:139], v[182:185], v[52:55]
	v_mfma_f32_16x16x32_bf16 v[48:51], v[144:147], v[182:185], v[48:51]
	v_mfma_f32_16x16x32_bf16 v[44:47], v[136:139], v[190:193], v[44:47]
	v_mfma_f32_16x16x32_bf16 v[40:43], v[144:147], v[190:193], v[40:43]
	v_mfma_f32_16x16x32_bf16 v[36:39], v[136:139], v[198:201], v[36:39]
	v_mfma_f32_16x16x32_bf16 v[32:35], v[144:147], v[198:201], v[32:35]
	s_setprio 0
	s_setprio 1
	v_mfma_f32_16x16x32_bf16 v[28:31], v[154:157], v[170:173], v[28:31]
	v_mfma_f32_16x16x32_bf16 v[24:27], v[162:165], v[170:173], v[24:27]
	v_mfma_f32_16x16x32_bf16 v[20:23], v[154:157], v[178:181], v[20:23]
	v_mfma_f32_16x16x32_bf16 v[16:19], v[162:165], v[178:181], v[16:19]
	v_mfma_f32_16x16x32_bf16 v[12:15], v[154:157], v[186:189], v[12:15]
	v_mfma_f32_16x16x32_bf16 v[8:11], v[162:165], v[186:189], v[8:11]
	v_mfma_f32_16x16x32_bf16 v[4:7], v[154:157], v[194:197], v[4:7]
	v_mfma_f32_16x16x32_bf16 v[0:3], v[162:165], v[194:197], v[0:3]
	v_mfma_f32_16x16x32_bf16 v[28:31], v[158:161], v[174:177], v[28:31]
	v_mfma_f32_16x16x32_bf16 v[24:27], v[166:169], v[174:177], v[24:27]
	v_mfma_f32_16x16x32_bf16 v[20:23], v[158:161], v[182:185], v[20:23]
	v_mfma_f32_16x16x32_bf16 v[16:19], v[166:169], v[182:185], v[16:19]
	v_mfma_f32_16x16x32_bf16 v[12:15], v[158:161], v[190:193], v[12:15]
	v_mfma_f32_16x16x32_bf16 v[8:11], v[166:169], v[190:193], v[8:11]
	v_mfma_f32_16x16x32_bf16 v[4:7], v[158:161], v[198:201], v[4:7]
	v_mfma_f32_16x16x32_bf16 v[0:3], v[166:169], v[198:201], v[0:3]
	s_setprio 0
	s_barrier
	s_add_i32 s63, s63, 2
	s_add_u32 s9, s9, 0x10000
	s_addc_u32 s33, s33, 0
	s_add_u32 s47, s47, 0x100
	s_addc_u32 s62, s62, 0
	s_cmp_gt_u32 s63, 29
	s_cbranch_scc0 .LBB0_485
	s_and_b64 vcc, exec, s[44:45]
	s_cbranch_vccz .LBB0_488
	s_barrier

; #define PG8_STAGE(bufoff, gbase, voff) do { const __amdgpu_buffer_rsrc_t _rs = __builtin_amdgcn_make_buffer_rsrc((void*)(gbase), 0, 0x7fffffff, 0x00020000); _Pragma("unroll") for (int _i = 0; _i < 2; ++_i) \
;         __builtin_amdgcn_raw_ptr_buffer_load_lds(_rs, (LAS unsigned*)(lds + (bufoff) + ldsw + _i * 8192), 16, (int)(voff)[_i], 0, 0, 0); } while (0)
; #define PG8_WAIT_V(n) asm volatile("s_waitcnt vmcnt(" #n ")" ::: "memory")
; #define PG8_WAIT_L(n) asm volatile("s_waitcnt lgkmcnt(" #n ")" ::: "memory")
; #define PG8_BAR __builtin_amdgcn_s_barrier()
; #define PG8_SCHED __builtin_amdgcn_sched_barrier(0)
; template <class Epi, class Sched, bool F8 = false>
; __device__ __forceinline__ void gemm_phase(LAS unsigned char* lds, const int lda, const int ldb, const Sched& S, const Epi& E) {
;     ...
;             const char* a1 = cA + (size_t)(t + 1) * kstep;
;             const char* a2 = last ? nA : cA + (size_t)(t + 2) * kstep; const char* b2 = last ? nB : cB + (size_t)(t + 2) * kstepB;
;             const char* a3 = a2 + kstep; const char* b3 = b2 + kstepB;
;     ...
;             PG8_LDB(B0, 0, 0); PG8_LDB(B1, 0, 1); PG8_SCHED; PG8_LDA(At, 0, 0); PG8_STAGE(PG8_SA(1, 1), a1 + hstepA, voffA);
;             PG8_WAIT_V(8); PG8_WAIT_L(0); PG8_BAR; PG8_MMA(0, 0, At, B0); PG8_MMA(0, 1, At, B1); PG8_BAR; PG8_SCHED;
;             PG8_LDA(At, 0, 1); PG8_STAGE(PG8_SB(0, 0), b2, voffB); PG8_STAGE(PG8_SB(0, 1), b2 + hstepB, voffB); PG8_STAGE(PG8_SA(0, 0), a2, voffA);
;             PG8_WAIT_V(8); PG8_WAIT_L(0); PG8_BAR; PG8_MMA(1, 0, At, B0); PG8_MMA(1, 1, At, B1); PG8_BAR; PG8_SCHED;
.LBB0_632:
	ds_read_b128 v[132:135], v142
	ds_read_b128 v[148:151], v142 offset:1024
	ds_read_b128 v[152:155], v142 offset:2048
	ds_read_b128 v[156:159], v142 offset:3072
	ds_read_b128 v[160:163], v143
	ds_read_b128 v[164:167], v143 offset:1024
	ds_read_b128 v[168:171], v143 offset:2048
	ds_read_b128 v[172:175], v143 offset:3072
	s_add_u32 s4, vcc_lo, 0xfff00080
	s_addc_u32 s5, vcc_hi, -1
	s_cmp_eq_u32 s64, 60
	s_cselect_b32 s40, s68, s4
	s_cselect_b32 s19, s69, s5
	s_cselect_b32 s18, s71, s67
	s_cselect_b32 s36, s70, s51
	s_add_u32 s16, s40, 0x80
	s_addc_u32 s17, s19, 0
	s_and_b32 s5, vcc_hi, 0xffff
	s_mov_b32 s4, vcc_lo
	s_mov_b32 m0, s92
	ds_read_b128 v[176:179], v144
	ds_read_b128 v[180:183], v144 offset:1024
	ds_read_b128 v[184:187], v144 offset:2048
	ds_read_b128 v[188:191], v144 offset:3072
	ds_read_b128 v[192:195], v144 offset:4096
	ds_read_b128 v[196:199], v144 offset:5120
	ds_read_b128 v[200:203], v144 offset:6144
	ds_read_b128 v[204:207], v144 offset:7168
	buffer_load_dwordx4 v138, s[4:7], 0 offen lds
	s_mov_b32 m0, s93
	s_nop 0
	buffer_load_dwordx4 v140, s[4:7], 0 offen lds
	s_waitcnt vmcnt(8)
	s_waitcnt lgkmcnt(0)
	s_barrier
	s_setprio 1
	v_mfma_f32_16x16x32_bf16 v[124:127], v[132:135], v[176:179], v[124:127]
	v_mfma_f32_16x16x32_bf16 v[120:123], v[152:155], v[176:179], v[120:123]
	v_mfma_f32_16x16x32_bf16 v[108:111], v[132:135], v[184:187], v[108:111]
	v_mfma_f32_16x16x32_bf16 v[104:107], v[152:155], v[184:187], v[104:107]
	v_mfma_f32_16x16x32_bf16 v[92:95], v[132:135], v[192:195], v[92:95]
	v_mfma_f32_16x16x32_bf16 v[88:91], v[152:155], v[192:195], v[88:91]
	v_mfma_f32_16x16x32_bf16 v[76:79], v[132:135], v[200:203], v[76:79]
	v_mfma_f32_16x16x32_bf16 v[72:75], v[152:155], v[200:203], v[72:75]
	v_mfma_f32_16x16x32_bf16 v[124:127], v[148:151], v[180:183], v[124:127]
	v_mfma_f32_16x16x32_bf16 v[120:123], v[156:159], v[180:183], v[120:123]
	v_mfma_f32_16x16x32_bf16 v[108:111], v[148:151], v[188:191], v[108:111]
	v_mfma_f32_16x16x32_bf16 v[104:107], v[156:159], v[188:191], v[104:107]
	v_mfma_f32_16x16x32_bf16 v[92:95], v[148:151], v[196:199], v[92:95]
	v_mfma_f32_16x16x32_bf16 v[88:91], v[156:159], v[196:199], v[88:91]
	v_mfma_f32_16x16x32_bf16 v[76:79], v[148:151], v[204:207], v[76:79]
	v_mfma_f32_16x16x32_bf16 v[72:75], v[156:159], v[204:207], v[72:75]
	s_setprio 0
	s_setprio 1
	v_mfma_f32_16x16x32_bf16 v[116:119], v[160:163], v[176:179], v[116:119]
	v_mfma_f32_16x16x32_bf16 v[112:115], v[168:171], v[176:179], v[112:115]
	v_mfma_f32_16x16x32_bf16 v[100:103], v[160:163], v[184:187], v[100:103]
	v_mfma_f32_16x16x32_bf16 v[96:99], v[168:171], v[184:187], v[96:99]
	v_mfma_f32_16x16x32_bf16 v[84:87], v[160:163], v[192:195], v[84:87]
	v_mfma_f32_16x16x32_bf16 v[80:83], v[168:171], v[192:195], v[80:83]
	v_mfma_f32_16x16x32_bf16 v[68:71], v[160:163], v[200:203], v[68:71]
	v_mfma_f32_16x16x32_bf16 v[64:67], v[168:171], v[200:203], v[64:67]
	v_mfma_f32_16x16x32_bf16 v[116:119], v[164:167], v[180:183], v[116:119]
	v_mfma_f32_16x16x32_bf16 v[112:115], v[172:175], v[180:183], v[112:115]
	v_mfma_f32_16x16x32_bf16 v[100:103], v[164:167], v[188:191], v[100:103]
	v_mfma_f32_16x16x32_bf16 v[96:99], v[172:175], v[188:191], v[96:99]
	v_mfma_f32_16x16x32_bf16 v[84:87], v[164:167], v[196:199], v[84:87]
	v_mfma_f32_16x16x32_bf16 v[80:83], v[172:175], v[196:199], v[80:83]
	v_mfma_f32_16x16x32_bf16 v[68:71], v[164:167], v[204:207], v[68:71]
	v_mfma_f32_16x16x32_bf16 v[64:67], v[172:175], v[204:207], v[64:67]
	s_setprio 0
	s_barrier
	s_and_b32 s37, s18, 0xffff
	s_mov_b32 m0, s73
	s_mov_b32 s38, s6
	s_mov_b32 s39, s7
	s_add_u32 s4, s36, 0x4000
	ds_read_b128 v[176:179], v144 offset:16384
	ds_read_b128 v[180:183], v144 offset:17408
	ds_read_b128 v[184:187], v144 offset:18432
	ds_read_b128 v[188:191], v144 offset:19456
	ds_read_b128 v[192:195], v144 offset:20480
	ds_read_b128 v[196:199], v144 offset:21504
	ds_read_b128 v[200:203], v144 offset:22528
	ds_read_b128 v[204:207], v144 offset:23552
	buffer_load_dwordx4 v139, s[36:39], 0 offen lds
	s_mov_b32 m0, s74
	s_addc_u32 s5, s18, 0
	buffer_load_dwordx4 v141, s[36:39], 0 offen lds
	s_and_b32 s5, s5, 0xffff
	s_mov_b32 m0, s75
	s_and_b32 s41, s19, 0xffff
	buffer_load_dwordx4 v139, s[4:7], 0 offen lds
	s_mov_b32 m0, s76
	s_mov_b32 s42, s6
	buffer_load_dwordx4 v141, s[4:7], 0 offen lds
	s_mov_b32 s43, s7
	s_mov_b32 m0, s61
	s_nop 0
	buffer_load_dwordx4 v138, s[40:43], 0 offen lds
	s_mov_b32 m0, s77
	s_nop 0
	buffer_load_dwordx4 v140, s[40:43], 0 offen lds
	s_nop 0
	s_waitcnt vmcnt(8)
	s_waitcnt lgkmcnt(0)
	s_barrier
; #define PG8_STAGE(bufoff, gbase, voff) do { const __amdgpu_buffer_rsrc_t _rs = __builtin_amdgcn_make_buffer_rsrc((void*)(gbase), 0, 0x7fffffff, 0x00020000); _Pragma("unroll") for (int _i = 0; _i < 2; ++_i) \
;         __builtin_amdgcn_raw_ptr_buffer_load_lds(_rs, (LAS unsigned*)(lds + (bufoff) + ldsw + _i * 8192), 16, (int)(voff)[_i], 0, 0, 0); } while (0)
; #define PG8_WAIT_V(n) asm volatile("s_waitcnt vmcnt(" #n ")" ::: "memory")
; #define PG8_WAIT_L(n) asm volatile("s_waitcnt lgkmcnt(" #n ")" ::: "memory")
; #define PG8_BAR __builtin_amdgcn_s_barrier()
; #define PG8_SCHED __builtin_amdgcn_sched_barrier(0)
; template <class Epi, class Sched, bool F8 = false>
; __device__ __forceinline__ void gemm_phase(LAS unsigned char* lds, const int lda, const int ldb, const Sched& S, const Epi& E) {
;     ...
;             PG8_WAIT_V(8); PG8_WAIT_L(0); PG8_BAR; PG8_MMA(1, 0, At, B0); PG8_MMA(1, 1, At, B1); PG8_BAR; PG8_SCHED;
;             PG8_LDB(B0, 1, 0); PG8_LDB(B1, 1, 1); PG8_SCHED; PG8_LDA(At, 1, 0); PG8_STAGE(PG8_SA(0, 1), a2 + hstepA, voffA);
;             PG8_WAIT_V(8); PG8_WAIT_L(0); PG8_BAR; PG8_MMA(0, 0, At, B0); PG8_MMA(0, 1, At, B1); PG8_BAR; PG8_SCHED;
	s_setprio 1
	v_mfma_f32_16x16x32_bf16 v[60:63], v[132:135], v[176:179], v[60:63]
	v_mfma_f32_16x16x32_bf16 v[56:59], v[152:155], v[176:179], v[56:59]
	v_mfma_f32_16x16x32_bf16 v[44:47], v[132:135], v[184:187], v[44:47]
	v_mfma_f32_16x16x32_bf16 v[40:43], v[152:155], v[184:187], v[40:43]
	v_mfma_f32_16x16x32_bf16 v[28:31], v[132:135], v[192:195], v[28:31]
	v_mfma_f32_16x16x32_bf16 v[24:27], v[152:155], v[192:195], v[24:27]
	v_mfma_f32_16x16x32_bf16 v[12:15], v[132:135], v[200:203], v[12:15]
	v_mfma_f32_16x16x32_bf16 v[8:11], v[152:155], v[200:203], v[8:11]
	v_mfma_f32_16x16x32_bf16 v[60:63], v[148:151], v[180:183], v[60:63]
	v_mfma_f32_16x16x32_bf16 v[56:59], v[156:159], v[180:183], v[56:59]
	v_mfma_f32_16x16x32_bf16 v[44:47], v[148:151], v[188:191], v[44:47]
	v_mfma_f32_16x16x32_bf16 v[40:43], v[156:159], v[188:191], v[40:43]
	v_mfma_f32_16x16x32_bf16 v[28:31], v[148:151], v[196:199], v[28:31]
	v_mfma_f32_16x16x32_bf16 v[24:27], v[156:159], v[196:199], v[24:27]
	v_mfma_f32_16x16x32_bf16 v[12:15], v[148:151], v[204:207], v[12:15]
	v_mfma_f32_16x16x32_bf16 v[8:11], v[156:159], v[204:207], v[8:11]
	s_setprio 0
	s_setprio 1
	v_mfma_f32_16x16x32_bf16 v[52:55], v[160:163], v[176:179], v[52:55]
	v_mfma_f32_16x16x32_bf16 v[48:51], v[168:171], v[176:179], v[48:51]
	v_mfma_f32_16x16x32_bf16 v[36:39], v[160:163], v[184:187], v[36:39]
	v_mfma_f32_16x16x32_bf16 v[32:35], v[168:171], v[184:187], v[32:35]
	v_mfma_f32_16x16x32_bf16 v[20:23], v[160:163], v[192:195], v[20:23]
	v_mfma_f32_16x16x32_bf16 v[16:19], v[168:171], v[192:195], v[16:19]
	v_mfma_f32_16x16x32_bf16 v[4:7], v[160:163], v[200:203], v[4:7]
	v_mfma_f32_16x16x32_bf16 v[0:3], v[168:171], v[200:203], v[0:3]
	v_mfma_f32_16x16x32_bf16 v[52:55], v[164:167], v[180:183], v[52:55]
	v_mfma_f32_16x16x32_bf16 v[48:51], v[172:175], v[180:183], v[48:51]
	v_mfma_f32_16x16x32_bf16 v[36:39], v[164:167], v[188:191], v[36:39]
	v_mfma_f32_16x16x32_bf16 v[32:35], v[172:175], v[188:191], v[32:35]
	v_mfma_f32_16x16x32_bf16 v[20:23], v[164:167], v[196:199], v[20:23]
	v_mfma_f32_16x16x32_bf16 v[16:19], v[172:175], v[196:199], v[16:19]
	v_mfma_f32_16x16x32_bf16 v[4:7], v[164:167], v[204:207], v[4:7]
	v_mfma_f32_16x16x32_bf16 v[0:3], v[172:175], v[204:207], v[0:3]
	s_setprio 0
	s_barrier
	ds_read_b128 v[132:135], v145
	ds_read_b128 v[148:151], v145 offset:1024
	ds_read_b128 v[152:155], v145 offset:2048
	ds_read_b128 v[156:159], v145 offset:3072
	ds_read_b128 v[160:163], v146
	ds_read_b128 v[164:167], v146 offset:1024
	ds_read_b128 v[168:171], v146 offset:2048
	ds_read_b128 v[172:175], v146 offset:3072
	s_add_u32 s4, s40, 0x100000
	s_addc_u32 s5, s19, 0
	s_and_b32 s5, s5, 0xffff
	s_mov_b32 m0, s78
	ds_read_b128 v[176:179], v144 offset:32768
	ds_read_b128 v[180:183], v144 offset:33792
	ds_read_b128 v[184:187], v144 offset:34816
	ds_read_b128 v[188:191], v144 offset:35840
	ds_read_b128 v[192:195], v144 offset:36864
	ds_read_b128 v[196:199], v144 offset:37888
	ds_read_b128 v[200:203], v144 offset:38912
	ds_read_b128 v[204:207], v144 offset:39936
	buffer_load_dwordx4 v138, s[4:7], 0 offen lds
	s_mov_b32 m0, s79
	s_nop 0
	buffer_load_dwordx4 v140, s[4:7], 0 offen lds
	s_waitcnt vmcnt(8)
	s_waitcnt lgkmcnt(0)
	s_barrier
	s_setprio 1
	v_mfma_f32_16x16x32_bf16 v[124:127], v[132:135], v[176:179], v[124:127]
	v_mfma_f32_16x16x32_bf16 v[120:123], v[152:155], v[176:179], v[120:123]
	v_mfma_f32_16x16x32_bf16 v[108:111], v[132:135], v[184:187], v[108:111]
	v_mfma_f32_16x16x32_bf16 v[104:107], v[152:155], v[184:187], v[104:107]
	v_mfma_f32_16x16x32_bf16 v[92:95], v[132:135], v[192:195], v[92:95]
	v_mfma_f32_16x16x32_bf16 v[88:91], v[152:155], v[192:195], v[88:91]
	v_mfma_f32_16x16x32_bf16 v[76:79], v[132:135], v[200:203], v[76:79]
	v_mfma_f32_16x16x32_bf16 v[72:75], v[152:155], v[200:203], v[72:75]
	v_mfma_f32_16x16x32_bf16 v[124:127], v[148:151], v[180:183], v[124:127]
	v_mfma_f32_16x16x32_bf16 v[120:123], v[156:159], v[180:183], v[120:123]
	v_mfma_f32_16x16x32_bf16 v[108:111], v[148:151], v[188:191], v[108:111]
	v_mfma_f32_16x16x32_bf16 v[104:107], v[156:159], v[188:191], v[104:107]
	v_mfma_f32_16x16x32_bf16 v[92:95], v[148:151], v[196:199], v[92:95]
	v_mfma_f32_16x16x32_bf16 v[88:91], v[156:159], v[196:199], v[88:91]
	v_mfma_f32_16x16x32_bf16 v[76:79], v[148:151], v[204:207], v[76:79]
	v_mfma_f32_16x16x32_bf16 v[72:75], v[156:159], v[204:207], v[72:75]
	s_setprio 0
	s_setprio 1
	v_mfma_f32_16x16x32_bf16 v[116:119], v[160:163], v[176:179], v[116:119]
	v_mfma_f32_16x16x32_bf16 v[112:115], v[168:171], v[176:179], v[112:115]
	v_mfma_f32_16x16x32_bf16 v[100:103], v[160:163], v[184:187], v[100:103]
	v_mfma_f32_16x16x32_bf16 v[96:99], v[168:171], v[184:187], v[96:99]
	v_mfma_f32_16x16x32_bf16 v[84:87], v[160:163], v[192:195], v[84:87]
	v_mfma_f32_16x16x32_bf16 v[80:83], v[168:171], v[192:195], v[80:83]
	v_mfma_f32_16x16x32_bf16 v[68:71], v[160:163], v[200:203], v[68:71]
	v_mfma_f32_16x16x32_bf16 v[64:67], v[168:171], v[200:203], v[64:67]
	v_mfma_f32_16x16x32_bf16 v[116:119], v[164:167], v[180:183], v[116:119]
	v_mfma_f32_16x16x32_bf16 v[112:115], v[172:175], v[180:183], v[112:115]
	v_mfma_f32_16x16x32_bf16 v[100:103], v[164:167], v[188:191], v[100:103]
	v_mfma_f32_16x16x32_bf16 v[96:99], v[172:175], v[188:191], v[96:99]
	v_mfma_f32_16x16x32_bf16 v[84:87], v[164:167], v[196:199], v[84:87]
	v_mfma_f32_16x16x32_bf16 v[80:83], v[172:175], v[196:199], v[80:83]
	v_mfma_f32_16x16x32_bf16 v[68:71], v[164:167], v[204:207], v[68:71]
	v_mfma_f32_16x16x32_bf16 v[64:67], v[172:175], v[204:207], v[64:67]
	s_setprio 0
	s_barrier
; #define PG8_STAGE(bufoff, gbase, voff) do { const __amdgpu_buffer_rsrc_t _rs = __builtin_amdgcn_make_buffer_rsrc((void*)(gbase), 0, 0x7fffffff, 0x00020000); _Pragma("unroll") for (int _i = 0; _i < 2; ++_i) \
;         __builtin_amdgcn_raw_ptr_buffer_load_lds(_rs, (LAS unsigned*)(lds + (bufoff) + ldsw + _i * 8192), 16, (int)(voff)[_i], 0, 0, 0); } while (0)
; #define PG8_WAIT_V(n) asm volatile("s_waitcnt vmcnt(" #n ")" ::: "memory")
; #define PG8_WAIT_L(n) asm volatile("s_waitcnt lgkmcnt(" #n ")" ::: "memory")
; #define PG8_BAR __builtin_amdgcn_s_barrier()
; #define PG8_SCHED __builtin_amdgcn_sched_barrier(0)
; template <class Epi, class Sched, bool F8 = false>
; __device__ __forceinline__ void gemm_phase(LAS unsigned char* lds, const int lda, const int ldb, const Sched& S, const Epi& E) {
;     ...
;             PG8_LDA(At, 1, 1); PG8_STAGE(PG8_SB(1, 0), b3, voffB); PG8_STAGE(PG8_SB(1, 1), b3 + hstepB, voffB); PG8_STAGE(PG8_SA(1, 0), a3, voffA);
;             PG8_WAIT_V(8); PG8_WAIT_L(0); PG8_BAR; PG8_MMA(1, 0, At, B0); PG8_MMA(1, 1, At, B1); PG8_BAR; PG8_SCHED;
;     ...
;         }
;         if (wr == 0) PG8_BAR;
	s_add_u32 s4, s36, 0x8000
	s_addc_u32 s5, s18, 0
	s_mov_b32 m0, s86
	s_and_b32 s5, s5, 0xffff
	ds_read_b128 v[176:179], v144 offset:49152
	ds_read_b128 v[180:183], v144 offset:50176
	ds_read_b128 v[184:187], v144 offset:51200
	ds_read_b128 v[188:191], v144 offset:52224
	ds_read_b128 v[192:195], v144 offset:53248
	ds_read_b128 v[196:199], v144 offset:54272
	ds_read_b128 v[200:203], v144 offset:55296
	ds_read_b128 v[204:207], v144 offset:56320
	buffer_load_dwordx4 v139, s[4:7], 0 offen lds
	s_mov_b32 m0, s87
	s_mov_b32 s19, s7
	buffer_load_dwordx4 v141, s[4:7], 0 offen lds
	s_add_u32 s4, s36, 0xc000
	s_addc_u32 s5, s18, 0
	s_and_b32 s5, s5, 0xffff
	s_mov_b32 m0, s90
	s_and_b32 s17, s17, 0xffff
	buffer_load_dwordx4 v139, s[4:7], 0 offen lds
	s_mov_b32 m0, s91
	s_mov_b32 s18, s6
	buffer_load_dwordx4 v141, s[4:7], 0 offen lds
	s_mov_b32 m0, s88
	s_nop 0
	buffer_load_dwordx4 v138, s[16:19], 0 offen lds
	s_mov_b32 m0, s89
	s_nop 0
	buffer_load_dwordx4 v140, s[16:19], 0 offen lds
	s_waitcnt vmcnt(8)
	s_waitcnt lgkmcnt(0)
	s_barrier
	s_setprio 1
	v_mfma_f32_16x16x32_bf16 v[60:63], v[132:135], v[176:179], v[60:63]
	v_mfma_f32_16x16x32_bf16 v[56:59], v[152:155], v[176:179], v[56:59]
	v_mfma_f32_16x16x32_bf16 v[44:47], v[132:135], v[184:187], v[44:47]
	v_mfma_f32_16x16x32_bf16 v[40:43], v[152:155], v[184:187], v[40:43]
	v_mfma_f32_16x16x32_bf16 v[28:31], v[132:135], v[192:195], v[28:31]
	v_mfma_f32_16x16x32_bf16 v[24:27], v[152:155], v[192:195], v[24:27]
	v_mfma_f32_16x16x32_bf16 v[12:15], v[132:135], v[200:203], v[12:15]
	v_mfma_f32_16x16x32_bf16 v[8:11], v[152:155], v[200:203], v[8:11]
	v_mfma_f32_16x16x32_bf16 v[60:63], v[148:151], v[180:183], v[60:63]
	v_mfma_f32_16x16x32_bf16 v[56:59], v[156:159], v[180:183], v[56:59]
	v_mfma_f32_16x16x32_bf16 v[44:47], v[148:151], v[188:191], v[44:47]
	v_mfma_f32_16x16x32_bf16 v[40:43], v[156:159], v[188:191], v[40:43]
	v_mfma_f32_16x16x32_bf16 v[28:31], v[148:151], v[196:199], v[28:31]
	v_mfma_f32_16x16x32_bf16 v[24:27], v[156:159], v[196:199], v[24:27]
	v_mfma_f32_16x16x32_bf16 v[12:15], v[148:151], v[204:207], v[12:15]
	v_mfma_f32_16x16x32_bf16 v[8:11], v[156:159], v[204:207], v[8:11]
	s_setprio 0
	s_setprio 1
	v_mfma_f32_16x16x32_bf16 v[52:55], v[160:163], v[176:179], v[52:55]
	v_mfma_f32_16x16x32_bf16 v[48:51], v[168:171], v[176:179], v[48:51]
	v_mfma_f32_16x16x32_bf16 v[36:39], v[160:163], v[184:187], v[36:39]
	v_mfma_f32_16x16x32_bf16 v[32:35], v[168:171], v[184:187], v[32:35]
	v_mfma_f32_16x16x32_bf16 v[20:23], v[160:163], v[192:195], v[20:23]
	v_mfma_f32_16x16x32_bf16 v[16:19], v[168:171], v[192:195], v[16:19]
	v_mfma_f32_16x16x32_bf16 v[4:7], v[160:163], v[200:203], v[4:7]
	v_mfma_f32_16x16x32_bf16 v[0:3], v[168:171], v[200:203], v[0:3]
	v_mfma_f32_16x16x32_bf16 v[52:55], v[164:167], v[180:183], v[52:55]
	v_mfma_f32_16x16x32_bf16 v[48:51], v[172:175], v[180:183], v[48:51]
	v_mfma_f32_16x16x32_bf16 v[36:39], v[164:167], v[188:191], v[36:39]
	v_mfma_f32_16x16x32_bf16 v[32:35], v[172:175], v[188:191], v[32:35]
	v_mfma_f32_16x16x32_bf16 v[20:23], v[164:167], v[196:199], v[20:23]
	v_mfma_f32_16x16x32_bf16 v[16:19], v[172:175], v[196:199], v[16:19]
	v_mfma_f32_16x16x32_bf16 v[4:7], v[164:167], v[204:207], v[4:7]
	v_mfma_f32_16x16x32_bf16 v[0:3], v[172:175], v[204:207], v[0:3]
	s_setprio 0
	s_barrier
	s_add_i32 s64, s64, 2
	s_add_u32 s51, s51, 0x10000
	s_addc_u32 s67, s67, 0
	s_add_u32 vcc_lo, vcc_lo, 0x100
	s_addc_u32 vcc_hi, vcc_hi, 0
	s_cmp_gt_u32 s64, 61
	s_cbranch_scc0 .LBB0_632
	s_and_b64 vcc, exec, s[26:27]
	s_cbranch_vccz .LBB0_635
	s_barrier

; #define PG8_STAGE(bufoff, gbase, voff) do { const __amdgpu_buffer_rsrc_t _rs = __builtin_amdgcn_make_buffer_rsrc((void*)(gbase), 0, 0x7fffffff, 0x00020000); _Pragma("unroll") for (int _i = 0; _i < 2; ++_i) \
;         __builtin_amdgcn_raw_ptr_buffer_load_lds(_rs, (LAS unsigned*)(lds + (bufoff) + ldsw + _i * 8192), 16, (int)(voff)[_i], 0, 0, 0); } while (0)
; #define PG8_WAIT_V(n) asm volatile("s_waitcnt vmcnt(" #n ")" ::: "memory")
; #define PG8_WAIT_L(n) asm volatile("s_waitcnt lgkmcnt(" #n ")" ::: "memory")
; #define PG8_BAR __builtin_amdgcn_s_barrier()
; #define PG8_SCHED __builtin_amdgcn_sched_barrier(0)
; template <class Epi, class Sched, bool F8 = false>
; __device__ __forceinline__ void gemm_phase(LAS unsigned char* lds, const int lda, const int ldb, const Sched& S, const Epi& E) {
;     ...
;             const char* a1 = cA + (size_t)(t + 1) * kstep;
;             const char* a2 = last ? nA : cA + (size_t)(t + 2) * kstep; const char* b2 = last ? nB : cB + (size_t)(t + 2) * kstepB;
;             const char* a3 = a2 + kstep; const char* b3 = b2 + kstepB;
;     ...
;             PG8_LDB(B0, 0, 0); PG8_LDB(B1, 0, 1); PG8_SCHED; PG8_LDA(At, 0, 0); PG8_STAGE(PG8_SA(1, 1), a1 + hstepA, voffA);
;             PG8_WAIT_V(8); PG8_WAIT_L(0); PG8_BAR; PG8_MMA(0, 0, At, B0); PG8_MMA(0, 1, At, B1); PG8_BAR; PG8_SCHED;
;             PG8_LDA(At, 0, 1); PG8_STAGE(PG8_SB(0, 0), b2, voffB); PG8_STAGE(PG8_SB(0, 1), b2 + hstepB, voffB); PG8_STAGE(PG8_SA(0, 0), a2, voffA);
;             PG8_WAIT_V(8); PG8_WAIT_L(0); PG8_BAR; PG8_MMA(1, 0, At, B0); PG8_MMA(1, 1, At, B1); PG8_BAR; PG8_SCHED;
.LBB0_778:
	ds_read_b128 v[118:121], v194
	ds_read_b128 v[122:125], v194 offset:1024
	ds_read_b128 v[130:133], v194 offset:2048
	ds_read_b128 v[134:137], v194 offset:3072
	ds_read_b128 v[138:141], v195
	ds_read_b128 v[142:145], v195 offset:1024
	ds_read_b128 v[146:149], v195 offset:2048
	ds_read_b128 v[150:153], v195 offset:3072
	s_add_u32 s4, s33, 0xfff00080
	s_addc_u32 s5, s43, -1
	s_cmp_eq_u32 s45, 60
	s_cselect_b32 s20, s46, s4
	s_cselect_b32 s7, s47, s5
	s_cselect_b32 s6, s49, s9
	s_cselect_b32 s16, s48, s8
	s_add_u32 s4, s20, 0x80
	s_addc_u32 s5, s7, 0
	s_and_b32 s13, s43, 0xffff
	s_mov_b32 s12, s33
	s_mov_b32 m0, s84
	ds_read_b128 v[162:165], v196
	ds_read_b128 v[166:169], v196 offset:1024
	ds_read_b128 v[170:173], v196 offset:2048
	ds_read_b128 v[186:189], v196 offset:3072
	ds_read_b128 v[200:203], v196 offset:4096
	ds_read_b128 v[204:207], v196 offset:5120
	ds_read_b128 v[208:211], v196 offset:6144
	ds_read_b128 v[212:215], v196 offset:7168
	buffer_load_dwordx4 v175, s[12:15], 0 offen lds
	s_mov_b32 m0, s86
	s_nop 0
	buffer_load_dwordx4 v179, s[12:15], 0 offen lds
	s_nop 0
	s_waitcnt vmcnt(8)
	s_waitcnt lgkmcnt(0)
	s_barrier
	s_setprio 1
	v_mfma_f32_16x16x32_bf16 v[158:161], v[118:121], v[162:165], v[158:161]
	v_mfma_f32_16x16x32_bf16 v[60:63], v[130:133], v[162:165], v[60:63]
	v_mfma_f32_16x16x32_bf16 v[154:157], v[118:121], v[170:173], v[154:157]
	v_mfma_f32_16x16x32_bf16 v[52:55], v[130:133], v[170:173], v[52:55]
	v_mfma_f32_16x16x32_bf16 v[114:117], v[118:121], v[200:203], v[114:117]
	v_mfma_f32_16x16x32_bf16 v[44:47], v[130:133], v[200:203], v[44:47]
	v_mfma_f32_16x16x32_bf16 v[108:111], v[118:121], v[208:211], v[110:113]
	v_mfma_f32_16x16x32_bf16 v[36:39], v[130:133], v[208:211], v[36:39]
	v_mfma_f32_16x16x32_bf16 v[158:161], v[122:125], v[166:169], v[158:161]
	v_mfma_f32_16x16x32_bf16 v[60:63], v[134:137], v[166:169], v[60:63]
	v_mfma_f32_16x16x32_bf16 v[154:157], v[122:125], v[186:189], v[154:157]
	v_mfma_f32_16x16x32_bf16 v[52:55], v[134:137], v[186:189], v[52:55]
	v_mfma_f32_16x16x32_bf16 v[114:117], v[122:125], v[204:207], v[114:117]
	v_mfma_f32_16x16x32_bf16 v[44:47], v[134:137], v[204:207], v[44:47]
	v_mfma_f32_16x16x32_bf16 v[108:111], v[122:125], v[212:215], v[108:111]
	v_mfma_f32_16x16x32_bf16 v[36:39], v[134:137], v[212:215], v[36:39]
	s_setprio 0
	s_setprio 1
	v_mfma_f32_16x16x32_bf16 v[104:107], v[138:141], v[162:165], v[104:107]
	v_mfma_f32_16x16x32_bf16 v[56:59], v[146:149], v[162:165], v[56:59]
	v_mfma_f32_16x16x32_bf16 v[126:129], v[138:141], v[170:173], v[126:129]
	v_mfma_f32_16x16x32_bf16 v[48:51], v[146:149], v[170:173], v[48:51]
	v_mfma_f32_16x16x32_bf16 v[100:103], v[138:141], v[200:203], v[100:103]
	v_mfma_f32_16x16x32_bf16 v[40:43], v[146:149], v[200:203], v[40:43]
	v_mfma_f32_16x16x32_bf16 v[96:99], v[138:141], v[208:211], v[96:99]
	v_mfma_f32_16x16x32_bf16 v[32:35], v[146:149], v[208:211], v[32:35]
	v_mfma_f32_16x16x32_bf16 v[104:107], v[142:145], v[166:169], v[104:107]
	v_mfma_f32_16x16x32_bf16 v[56:59], v[150:153], v[166:169], v[56:59]
	v_mfma_f32_16x16x32_bf16 v[126:129], v[142:145], v[186:189], v[126:129]
	v_mfma_f32_16x16x32_bf16 v[48:51], v[150:153], v[186:189], v[48:51]
	v_mfma_f32_16x16x32_bf16 v[100:103], v[142:145], v[204:207], v[100:103]
	v_mfma_f32_16x16x32_bf16 v[40:43], v[150:153], v[204:207], v[40:43]
	v_mfma_f32_16x16x32_bf16 v[96:99], v[142:145], v[212:215], v[96:99]
	v_mfma_f32_16x16x32_bf16 v[32:35], v[150:153], v[212:215], v[32:35]
	s_setprio 0
	s_barrier
	s_and_b32 s17, s6, 0xffff
	s_mov_b32 m0, s68
	s_mov_b32 s18, s14
	s_mov_b32 s19, s15
	s_add_u32 s12, s16, 0x4000
	ds_read_b128 v[162:165], v196 offset:16384
	ds_read_b128 v[166:169], v196 offset:17408
	ds_read_b128 v[170:173], v196 offset:18432
	ds_read_b128 v[186:189], v196 offset:19456
	ds_read_b128 v[200:203], v196 offset:20480
	ds_read_b128 v[204:207], v196 offset:21504
	ds_read_b128 v[208:211], v196 offset:22528
	ds_read_b128 v[212:215], v196 offset:23552
	buffer_load_dwordx4 v177, s[16:19], 0 offen lds
	s_mov_b32 m0, s69
	s_addc_u32 s13, s6, 0
	buffer_load_dwordx4 v193, s[16:19], 0 offen lds
	s_and_b32 s13, s13, 0xffff
	s_mov_b32 m0, s70
	s_and_b32 s21, s7, 0xffff
	buffer_load_dwordx4 v177, s[12:15], 0 offen lds
	s_mov_b32 m0, s71
	s_mov_b32 s22, s14
	buffer_load_dwordx4 v193, s[12:15], 0 offen lds
	s_mov_b32 s23, s15
	s_mov_b32 m0, s51
	s_nop 0
	buffer_load_dwordx4 v175, s[20:23], 0 offen lds
	s_mov_b32 m0, s72
	s_nop 0
	buffer_load_dwordx4 v179, s[20:23], 0 offen lds
	s_nop 0
	s_waitcnt vmcnt(8)
	s_waitcnt lgkmcnt(0)
	s_barrier
; #define PG8_STAGE(bufoff, gbase, voff) do { const __amdgpu_buffer_rsrc_t _rs = __builtin_amdgcn_make_buffer_rsrc((void*)(gbase), 0, 0x7fffffff, 0x00020000); _Pragma("unroll") for (int _i = 0; _i < 2; ++_i) \
;         __builtin_amdgcn_raw_ptr_buffer_load_lds(_rs, (LAS unsigned*)(lds + (bufoff) + ldsw + _i * 8192), 16, (int)(voff)[_i], 0, 0, 0); } while (0)
; #define PG8_WAIT_V(n) asm volatile("s_waitcnt vmcnt(" #n ")" ::: "memory")
; #define PG8_WAIT_L(n) asm volatile("s_waitcnt lgkmcnt(" #n ")" ::: "memory")
; #define PG8_BAR __builtin_amdgcn_s_barrier()
; #define PG8_SCHED __builtin_amdgcn_sched_barrier(0)
; template <class Epi, class Sched, bool F8 = false>
; __device__ __forceinline__ void gemm_phase(LAS unsigned char* lds, const int lda, const int ldb, const Sched& S, const Epi& E) {
;     ...
;             PG8_WAIT_V(8); PG8_WAIT_L(0); PG8_BAR; PG8_MMA(1, 0, At, B0); PG8_MMA(1, 1, At, B1); PG8_BAR; PG8_SCHED;
;             PG8_LDB(B0, 1, 0); PG8_LDB(B1, 1, 1); PG8_SCHED; PG8_LDA(At, 1, 0); PG8_STAGE(PG8_SA(0, 1), a2 + hstepA, voffA);
;             PG8_WAIT_V(8); PG8_WAIT_L(0); PG8_BAR; PG8_MMA(0, 0, At, B0); PG8_MMA(0, 1, At, B1); PG8_BAR; PG8_SCHED;
	s_setprio 1
	v_mfma_f32_16x16x32_bf16 v[92:95], v[118:121], v[162:165], v[92:95]
	v_mfma_f32_16x16x32_bf16 v[28:31], v[130:133], v[162:165], v[28:31]
	v_mfma_f32_16x16x32_bf16 v[84:87], v[118:121], v[170:173], v[84:87]
	v_mfma_f32_16x16x32_bf16 v[20:23], v[130:133], v[170:173], v[20:23]
	v_mfma_f32_16x16x32_bf16 v[76:79], v[118:121], v[200:203], v[76:79]
	v_mfma_f32_16x16x32_bf16 v[12:15], v[130:133], v[200:203], v[12:15]
	v_mfma_f32_16x16x32_bf16 v[72:75], v[118:121], v[208:211], v[72:75]
	v_mfma_f32_16x16x32_bf16 v[4:7], v[130:133], v[208:211], v[4:7]
	v_mfma_f32_16x16x32_bf16 v[92:95], v[122:125], v[166:169], v[92:95]
	v_mfma_f32_16x16x32_bf16 v[28:31], v[134:137], v[166:169], v[28:31]
	v_mfma_f32_16x16x32_bf16 v[84:87], v[122:125], v[186:189], v[84:87]
	v_mfma_f32_16x16x32_bf16 v[20:23], v[134:137], v[186:189], v[20:23]
	v_mfma_f32_16x16x32_bf16 v[76:79], v[122:125], v[204:207], v[76:79]
	v_mfma_f32_16x16x32_bf16 v[12:15], v[134:137], v[204:207], v[12:15]
	v_mfma_f32_16x16x32_bf16 v[72:75], v[122:125], v[212:215], v[72:75]
	v_mfma_f32_16x16x32_bf16 v[4:7], v[134:137], v[212:215], v[4:7]
	s_setprio 0
	s_setprio 1
	v_mfma_f32_16x16x32_bf16 v[88:91], v[138:141], v[162:165], v[88:91]
	v_mfma_f32_16x16x32_bf16 v[24:27], v[146:149], v[162:165], v[24:27]
	v_mfma_f32_16x16x32_bf16 v[80:83], v[138:141], v[170:173], v[80:83]
	v_mfma_f32_16x16x32_bf16 v[16:19], v[146:149], v[170:173], v[16:19]
	v_mfma_f32_16x16x32_bf16 v[68:71], v[138:141], v[200:203], v[68:71]
	v_mfma_f32_16x16x32_bf16 v[8:11], v[146:149], v[200:203], v[8:11]
	v_mfma_f32_16x16x32_bf16 v[64:67], v[138:141], v[208:211], v[64:67]
	v_mfma_f32_16x16x32_bf16 v[0:3], v[146:149], v[208:211], v[0:3]
	v_mfma_f32_16x16x32_bf16 v[88:91], v[142:145], v[166:169], v[88:91]
	v_mfma_f32_16x16x32_bf16 v[24:27], v[150:153], v[166:169], v[24:27]
	v_mfma_f32_16x16x32_bf16 v[80:83], v[142:145], v[186:189], v[80:83]
	v_mfma_f32_16x16x32_bf16 v[16:19], v[150:153], v[186:189], v[16:19]
	v_mfma_f32_16x16x32_bf16 v[68:71], v[142:145], v[204:207], v[68:71]
	v_mfma_f32_16x16x32_bf16 v[8:11], v[150:153], v[204:207], v[8:11]
	v_mfma_f32_16x16x32_bf16 v[64:67], v[142:145], v[212:215], v[64:67]
	v_mfma_f32_16x16x32_bf16 v[0:3], v[150:153], v[212:215], v[0:3]
	s_setprio 0
	s_barrier
	ds_read_b128 v[118:121], v197
	ds_read_b128 v[122:125], v197 offset:1024
	ds_read_b128 v[130:133], v197 offset:2048
	ds_read_b128 v[134:137], v197 offset:3072
	ds_read_b128 v[138:141], v198
	ds_read_b128 v[142:145], v198 offset:1024
	ds_read_b128 v[146:149], v198 offset:2048
	ds_read_b128 v[150:153], v198 offset:3072
	s_add_u32 s12, s20, 0x100000
	s_addc_u32 s7, s7, 0
	s_and_b32 s13, s7, 0xffff
	s_mov_b32 m0, s73
	ds_read_b128 v[162:165], v196 offset:32768
	ds_read_b128 v[166:169], v196 offset:33792
	ds_read_b128 v[170:173], v196 offset:34816
	ds_read_b128 v[186:189], v196 offset:35840
	ds_read_b128 v[200:203], v196 offset:36864
	ds_read_b128 v[204:207], v196 offset:37888
	ds_read_b128 v[208:211], v196 offset:38912
	ds_read_b128 v[212:215], v196 offset:39936
	buffer_load_dwordx4 v175, s[12:15], 0 offen lds
	s_mov_b32 m0, s74
	s_nop 0
	buffer_load_dwordx4 v179, s[12:15], 0 offen lds
	s_waitcnt vmcnt(8)
	s_waitcnt lgkmcnt(0)
	s_barrier
	s_setprio 1
	v_mfma_f32_16x16x32_bf16 v[158:161], v[118:121], v[162:165], v[158:161]
	v_mfma_f32_16x16x32_bf16 v[60:63], v[130:133], v[162:165], v[60:63]
	v_mfma_f32_16x16x32_bf16 v[154:157], v[118:121], v[170:173], v[154:157]
	v_mfma_f32_16x16x32_bf16 v[52:55], v[130:133], v[170:173], v[52:55]
	v_mfma_f32_16x16x32_bf16 v[112:115], v[118:121], v[200:203], v[114:117]
	v_mfma_f32_16x16x32_bf16 v[44:47], v[130:133], v[200:203], v[44:47]
	v_mfma_f32_16x16x32_bf16 v[108:111], v[118:121], v[208:211], v[108:111]
	v_mfma_f32_16x16x32_bf16 v[36:39], v[130:133], v[208:211], v[36:39]
	v_mfma_f32_16x16x32_bf16 v[158:161], v[122:125], v[166:169], v[158:161]
	v_mfma_f32_16x16x32_bf16 v[60:63], v[134:137], v[166:169], v[60:63]
	v_mfma_f32_16x16x32_bf16 v[154:157], v[122:125], v[186:189], v[154:157]
	v_mfma_f32_16x16x32_bf16 v[52:55], v[134:137], v[186:189], v[52:55]
	v_mfma_f32_16x16x32_bf16 v[114:117], v[122:125], v[204:207], v[112:115]
	v_mfma_f32_16x16x32_bf16 v[44:47], v[134:137], v[204:207], v[44:47]
	v_mfma_f32_16x16x32_bf16 v[110:113], v[122:125], v[212:215], v[108:111]
	v_mfma_f32_16x16x32_bf16 v[36:39], v[134:137], v[212:215], v[36:39]
	s_setprio 0
	s_setprio 1
	v_mfma_f32_16x16x32_bf16 v[104:107], v[138:141], v[162:165], v[104:107]
	v_mfma_f32_16x16x32_bf16 v[56:59], v[146:149], v[162:165], v[56:59]
	v_mfma_f32_16x16x32_bf16 v[126:129], v[138:141], v[170:173], v[126:129]
	v_mfma_f32_16x16x32_bf16 v[48:51], v[146:149], v[170:173], v[48:51]
	v_mfma_f32_16x16x32_bf16 v[100:103], v[138:141], v[200:203], v[100:103]
	v_mfma_f32_16x16x32_bf16 v[40:43], v[146:149], v[200:203], v[40:43]
	v_mfma_f32_16x16x32_bf16 v[96:99], v[138:141], v[208:211], v[96:99]
	v_mfma_f32_16x16x32_bf16 v[32:35], v[146:149], v[208:211], v[32:35]
	v_mfma_f32_16x16x32_bf16 v[104:107], v[142:145], v[166:169], v[104:107]
	v_mfma_f32_16x16x32_bf16 v[56:59], v[150:153], v[166:169], v[56:59]
	v_mfma_f32_16x16x32_bf16 v[126:129], v[142:145], v[186:189], v[126:129]
	v_mfma_f32_16x16x32_bf16 v[48:51], v[150:153], v[186:189], v[48:51]
	v_mfma_f32_16x16x32_bf16 v[100:103], v[142:145], v[204:207], v[100:103]
	v_mfma_f32_16x16x32_bf16 v[40:43], v[150:153], v[204:207], v[40:43]
	v_mfma_f32_16x16x32_bf16 v[96:99], v[142:145], v[212:215], v[96:99]
	v_mfma_f32_16x16x32_bf16 v[32:35], v[150:153], v[212:215], v[32:35]
	s_setprio 0
	s_barrier
; #define PG8_STAGE(bufoff, gbase, voff) do { const __amdgpu_buffer_rsrc_t _rs = __builtin_amdgcn_make_buffer_rsrc((void*)(gbase), 0, 0x7fffffff, 0x00020000); _Pragma("unroll") for (int _i = 0; _i < 2; ++_i) \
;         __builtin_amdgcn_raw_ptr_buffer_load_lds(_rs, (LAS unsigned*)(lds + (bufoff) + ldsw + _i * 8192), 16, (int)(voff)[_i], 0, 0, 0); } while (0)
; #define PG8_WAIT_V(n) asm volatile("s_waitcnt vmcnt(" #n ")" ::: "memory")
; #define PG8_WAIT_L(n) asm volatile("s_waitcnt lgkmcnt(" #n ")" ::: "memory")
; #define PG8_BAR __builtin_amdgcn_s_barrier()
; #define PG8_SCHED __builtin_amdgcn_sched_barrier(0)
; template <class Epi, class Sched, bool F8 = false>
; __device__ __forceinline__ void gemm_phase(LAS unsigned char* lds, const int lda, const int ldb, const Sched& S, const Epi& E) {
;     ...
;             PG8_LDA(At, 1, 1); PG8_STAGE(PG8_SB(1, 0), b3, voffB); PG8_STAGE(PG8_SB(1, 1), b3 + hstepB, voffB); PG8_STAGE(PG8_SA(1, 0), a3, voffA);
;             PG8_WAIT_V(8); PG8_WAIT_L(0); PG8_BAR; PG8_MMA(1, 0, At, B0); PG8_MMA(1, 1, At, B1); PG8_BAR; PG8_SCHED;
;     ...
;         }
;         if (wr == 0) PG8_BAR;
	s_add_u32 s12, s16, 0x8000
	s_addc_u32 s7, s6, 0
	s_mov_b32 m0, s78
	s_and_b32 s13, s7, 0xffff
	ds_read_b128 v[162:165], v196 offset:49152
	ds_read_b128 v[166:169], v196 offset:50176
	ds_read_b128 v[170:173], v196 offset:51200
	ds_read_b128 v[186:189], v196 offset:52224
	ds_read_b128 v[200:203], v196 offset:53248
	ds_read_b128 v[204:207], v196 offset:54272
	ds_read_b128 v[208:211], v196 offset:55296
	ds_read_b128 v[212:215], v196 offset:56320
	buffer_load_dwordx4 v177, s[12:15], 0 offen lds
	s_mov_b32 m0, s79
	s_mov_b32 s7, s15
	buffer_load_dwordx4 v193, s[12:15], 0 offen lds
	s_add_u32 s12, s16, 0xc000
	s_addc_u32 s6, s6, 0
	s_and_b32 s13, s6, 0xffff
	s_mov_b32 m0, s82
	s_and_b32 s5, s5, 0xffff
	buffer_load_dwordx4 v177, s[12:15], 0 offen lds
	s_mov_b32 m0, s83
	s_mov_b32 s6, s14
	buffer_load_dwordx4 v193, s[12:15], 0 offen lds
	s_mov_b32 m0, s80
	s_nop 0
	buffer_load_dwordx4 v175, s[4:7], 0 offen lds
	s_mov_b32 m0, s81
	s_nop 0
	buffer_load_dwordx4 v179, s[4:7], 0 offen lds
	s_waitcnt vmcnt(8)
	s_waitcnt lgkmcnt(0)
	s_barrier
	s_setprio 1
	v_mfma_f32_16x16x32_bf16 v[92:95], v[118:121], v[162:165], v[92:95]
	v_mfma_f32_16x16x32_bf16 v[28:31], v[130:133], v[162:165], v[28:31]
	v_mfma_f32_16x16x32_bf16 v[84:87], v[118:121], v[170:173], v[84:87]
	v_mfma_f32_16x16x32_bf16 v[20:23], v[130:133], v[170:173], v[20:23]
	v_mfma_f32_16x16x32_bf16 v[76:79], v[118:121], v[200:203], v[76:79]
	v_mfma_f32_16x16x32_bf16 v[12:15], v[130:133], v[200:203], v[12:15]
	v_mfma_f32_16x16x32_bf16 v[72:75], v[118:121], v[208:211], v[72:75]
	v_mfma_f32_16x16x32_bf16 v[4:7], v[130:133], v[208:211], v[4:7]
	v_mfma_f32_16x16x32_bf16 v[92:95], v[122:125], v[166:169], v[92:95]
	v_mfma_f32_16x16x32_bf16 v[28:31], v[134:137], v[166:169], v[28:31]
	v_mfma_f32_16x16x32_bf16 v[84:87], v[122:125], v[186:189], v[84:87]
	v_mfma_f32_16x16x32_bf16 v[20:23], v[134:137], v[186:189], v[20:23]
	v_mfma_f32_16x16x32_bf16 v[76:79], v[122:125], v[204:207], v[76:79]
	v_mfma_f32_16x16x32_bf16 v[12:15], v[134:137], v[204:207], v[12:15]
	v_mfma_f32_16x16x32_bf16 v[72:75], v[122:125], v[212:215], v[72:75]
	v_mfma_f32_16x16x32_bf16 v[4:7], v[134:137], v[212:215], v[4:7]
	s_setprio 0
	s_setprio 1
	v_mfma_f32_16x16x32_bf16 v[88:91], v[138:141], v[162:165], v[88:91]
	v_mfma_f32_16x16x32_bf16 v[24:27], v[146:149], v[162:165], v[24:27]
	v_mfma_f32_16x16x32_bf16 v[80:83], v[138:141], v[170:173], v[80:83]
	v_mfma_f32_16x16x32_bf16 v[16:19], v[146:149], v[170:173], v[16:19]
	v_mfma_f32_16x16x32_bf16 v[68:71], v[138:141], v[200:203], v[68:71]
	v_mfma_f32_16x16x32_bf16 v[8:11], v[146:149], v[200:203], v[8:11]
	v_mfma_f32_16x16x32_bf16 v[64:67], v[138:141], v[208:211], v[64:67]
	v_mfma_f32_16x16x32_bf16 v[0:3], v[146:149], v[208:211], v[0:3]
	v_mfma_f32_16x16x32_bf16 v[88:91], v[142:145], v[166:169], v[88:91]
	v_mfma_f32_16x16x32_bf16 v[24:27], v[150:153], v[166:169], v[24:27]
	v_mfma_f32_16x16x32_bf16 v[80:83], v[142:145], v[186:189], v[80:83]
	v_mfma_f32_16x16x32_bf16 v[16:19], v[150:153], v[186:189], v[16:19]
	v_mfma_f32_16x16x32_bf16 v[68:71], v[142:145], v[204:207], v[68:71]
	v_mfma_f32_16x16x32_bf16 v[8:11], v[150:153], v[204:207], v[8:11]
	v_mfma_f32_16x16x32_bf16 v[64:67], v[142:145], v[212:215], v[64:67]
	v_mfma_f32_16x16x32_bf16 v[0:3], v[150:153], v[212:215], v[0:3]
	s_setprio 0
	s_barrier
	s_add_i32 s45, s45, 2
	s_add_u32 s8, s8, 0x10000
	s_addc_u32 s9, s9, 0
	s_add_u32 s33, s33, 0x100
	s_addc_u32 s43, s43, 0
	s_cmp_gt_u32 s45, 61
	s_cbranch_scc0 .LBB0_778
	s_and_b64 vcc, exec, s[40:41]
	s_cbranch_vccz .LBB0_781
	s_barrier

; #define PG8_STAGE(bufoff, gbase, voff) do { const __amdgpu_buffer_rsrc_t _rs = __builtin_amdgcn_make_buffer_rsrc((void*)(gbase), 0, 0x7fffffff, 0x00020000); _Pragma("unroll") for (int _i = 0; _i < 2; ++_i) \
;         __builtin_amdgcn_raw_ptr_buffer_load_lds(_rs, (LAS unsigned*)(lds + (bufoff) + ldsw + _i * 8192), 16, (int)(voff)[_i], 0, 0, 0); } while (0)
; #define PG8_WAIT_V(n) asm volatile("s_waitcnt vmcnt(" #n ")" ::: "memory")
; #define PG8_WAIT_L(n) asm volatile("s_waitcnt lgkmcnt(" #n ")" ::: "memory")
; #define PG8_BAR __builtin_amdgcn_s_barrier()
; #define PG8_SCHED __builtin_amdgcn_sched_barrier(0)
; template <class Epi, class Sched, bool F8 = false>
; __device__ __forceinline__ void gemm_phase(LAS unsigned char* lds, const int lda, const int ldb, const Sched& S, const Epi& E) {
;     ...
;             const char* a1 = cA + (size_t)(t + 1) * kstep;
;             const char* a2 = last ? nA : cA + (size_t)(t + 2) * kstep; const char* b2 = last ? nB : cB + (size_t)(t + 2) * kstepB;
;             const char* a3 = a2 + kstep; const char* b3 = b2 + kstepB;
;     ...
;             PG8_LDB(B0, 0, 0); PG8_LDB(B1, 0, 1); PG8_SCHED; PG8_LDA(At, 0, 0); PG8_STAGE(PG8_SA(1, 1), a1 + hstepA, voffA);
;             PG8_WAIT_V(8); PG8_WAIT_L(0); PG8_BAR; PG8_MMA(0, 0, At, B0); PG8_MMA(0, 1, At, B1); PG8_BAR; PG8_SCHED;
;             PG8_LDA(At, 0, 1); PG8_STAGE(PG8_SB(0, 0), b2, voffB); PG8_STAGE(PG8_SB(0, 1), b2 + hstepB, voffB); PG8_STAGE(PG8_SA(0, 0), a2, voffA);
;             PG8_WAIT_V(8); PG8_WAIT_L(0); PG8_BAR; PG8_MMA(1, 0, At, B0); PG8_MMA(1, 1, At, B1); PG8_BAR; PG8_SCHED;
.LBB0_935:
	ds_read_b128 v[136:139], v142
	ds_read_b128 v[148:151], v142 offset:1024
	ds_read_b128 v[152:155], v142 offset:2048
	ds_read_b128 v[156:159], v142 offset:3072
	ds_read_b128 v[160:163], v143
	ds_read_b128 v[164:167], v143 offset:1024
	ds_read_b128 v[168:171], v143 offset:2048
	ds_read_b128 v[180:183], v143 offset:3072
	s_add_u32 s4, s91, 0xffd50080
	s_addc_u32 s5, s92, -1
	s_cmpk_eq_i32 s64, 0xa8
	s_cselect_b32 s20, s44, s4
	s_cselect_b32 s15, s45, s5
	s_cselect_b32 s14, s47, s90
	s_cselect_b32 s16, s46, s89
	s_add_u32 s12, s20, 0x80
	s_addc_u32 s13, s15, 0
	s_and_b32 s5, s92, 0xffff
	s_mov_b32 s4, s91
	s_mov_b32 m0, s79
	ds_read_b128 v[184:187], v144
	ds_read_b128 v[188:191], v144 offset:1024
	ds_read_b128 v[194:197], v144 offset:2048
	ds_read_b128 v[198:201], v144 offset:3072
	ds_read_b128 v[202:205], v144 offset:4096
	ds_read_b128 v[206:209], v144 offset:5120
	ds_read_b128 v[210:213], v144 offset:6144
	ds_read_b128 v[214:217], v144 offset:7168
	buffer_load_dwordx4 v128, s[4:7], 0 offen lds
	s_mov_b32 m0, s80
	s_nop 0
	buffer_load_dwordx4 v130, s[4:7], 0 offen lds
	s_waitcnt vmcnt(8)
	s_waitcnt lgkmcnt(0)
	s_barrier
	s_setprio 1
	v_mfma_f32_16x16x32_bf16 v[124:127], v[136:139], v[184:187], v[124:127]
	v_mfma_f32_16x16x32_bf16 v[120:123], v[152:155], v[184:187], v[120:123]
	v_mfma_f32_16x16x32_bf16 v[108:111], v[136:139], v[194:197], v[108:111]
	v_mfma_f32_16x16x32_bf16 v[104:107], v[152:155], v[194:197], v[104:107]
	v_mfma_f32_16x16x32_bf16 v[92:95], v[136:139], v[202:205], v[92:95]
	v_mfma_f32_16x16x32_bf16 v[88:91], v[152:155], v[202:205], v[88:91]
	v_mfma_f32_16x16x32_bf16 v[76:79], v[136:139], v[210:213], v[76:79]
	v_mfma_f32_16x16x32_bf16 v[72:75], v[152:155], v[210:213], v[72:75]
	v_mfma_f32_16x16x32_bf16 v[124:127], v[148:151], v[188:191], v[124:127]
	v_mfma_f32_16x16x32_bf16 v[120:123], v[156:159], v[188:191], v[120:123]
	v_mfma_f32_16x16x32_bf16 v[108:111], v[148:151], v[198:201], v[108:111]
	v_mfma_f32_16x16x32_bf16 v[104:107], v[156:159], v[198:201], v[104:107]
	v_mfma_f32_16x16x32_bf16 v[92:95], v[148:151], v[206:209], v[92:95]
	v_mfma_f32_16x16x32_bf16 v[88:91], v[156:159], v[206:209], v[88:91]
	v_mfma_f32_16x16x32_bf16 v[76:79], v[148:151], v[214:217], v[76:79]
	v_mfma_f32_16x16x32_bf16 v[72:75], v[156:159], v[214:217], v[72:75]
	s_setprio 0
	s_setprio 1
	v_mfma_f32_16x16x32_bf16 v[116:119], v[160:163], v[184:187], v[116:119]
	v_mfma_f32_16x16x32_bf16 v[112:115], v[168:171], v[184:187], v[112:115]
	v_mfma_f32_16x16x32_bf16 v[100:103], v[160:163], v[194:197], v[100:103]
	v_mfma_f32_16x16x32_bf16 v[96:99], v[168:171], v[194:197], v[96:99]
	v_mfma_f32_16x16x32_bf16 v[84:87], v[160:163], v[202:205], v[84:87]
	v_mfma_f32_16x16x32_bf16 v[80:83], v[168:171], v[202:205], v[80:83]
	v_mfma_f32_16x16x32_bf16 v[68:71], v[160:163], v[210:213], v[68:71]
	v_mfma_f32_16x16x32_bf16 v[64:67], v[168:171], v[210:213], v[64:67]
	v_mfma_f32_16x16x32_bf16 v[116:119], v[164:167], v[188:191], v[116:119]
	v_mfma_f32_16x16x32_bf16 v[112:115], v[180:183], v[188:191], v[112:115]
	v_mfma_f32_16x16x32_bf16 v[100:103], v[164:167], v[198:201], v[100:103]
	v_mfma_f32_16x16x32_bf16 v[96:99], v[180:183], v[198:201], v[96:99]
	v_mfma_f32_16x16x32_bf16 v[84:87], v[164:167], v[206:209], v[84:87]
	v_mfma_f32_16x16x32_bf16 v[80:83], v[180:183], v[206:209], v[80:83]
	v_mfma_f32_16x16x32_bf16 v[68:71], v[164:167], v[214:217], v[68:71]
	v_mfma_f32_16x16x32_bf16 v[64:67], v[180:183], v[214:217], v[64:67]
	s_setprio 0
	s_barrier
	s_and_b32 s17, s14, 0xffff
	s_mov_b32 m0, s49
	s_mov_b32 s18, s6
	s_mov_b32 s19, s7
	s_add_u32 s4, s16, 0x4000
	ds_read_b128 v[184:187], v144 offset:16384
	ds_read_b128 v[188:191], v144 offset:17408
	ds_read_b128 v[194:197], v144 offset:18432
	ds_read_b128 v[198:201], v144 offset:19456
	ds_read_b128 v[202:205], v144 offset:20480
	ds_read_b128 v[206:209], v144 offset:21504
	ds_read_b128 v[210:213], v144 offset:22528
	ds_read_b128 v[214:217], v144 offset:23552
	buffer_load_dwordx4 v129, s[16:19], 0 offen lds
	s_mov_b32 m0, s50
	s_addc_u32 s5, s14, 0
	buffer_load_dwordx4 v131, s[16:19], 0 offen lds
	s_and_b32 s5, s5, 0xffff
	s_mov_b32 m0, s51
	s_and_b32 s21, s15, 0xffff
	buffer_load_dwordx4 v129, s[4:7], 0 offen lds
	s_mov_b32 m0, s52
	s_mov_b32 s22, s6
	buffer_load_dwordx4 v131, s[4:7], 0 offen lds
	s_mov_b32 s23, s7
	s_mov_b32 m0, s48
	s_nop 0
	buffer_load_dwordx4 v128, s[20:23], 0 offen lds
	s_mov_b32 m0, s53
	s_nop 0
	buffer_load_dwordx4 v130, s[20:23], 0 offen lds
	s_nop 0
	s_waitcnt vmcnt(8)
	s_waitcnt lgkmcnt(0)
	s_barrier
; #define PG8_STAGE(bufoff, gbase, voff) do { const __amdgpu_buffer_rsrc_t _rs = __builtin_amdgcn_make_buffer_rsrc((void*)(gbase), 0, 0x7fffffff, 0x00020000); _Pragma("unroll") for (int _i = 0; _i < 2; ++_i) \
;         __builtin_amdgcn_raw_ptr_buffer_load_lds(_rs, (LAS unsigned*)(lds + (bufoff) + ldsw + _i * 8192), 16, (int)(voff)[_i], 0, 0, 0); } while (0)
; #define PG8_WAIT_V(n) asm volatile("s_waitcnt vmcnt(" #n ")" ::: "memory")
; #define PG8_WAIT_L(n) asm volatile("s_waitcnt lgkmcnt(" #n ")" ::: "memory")
; #define PG8_BAR __builtin_amdgcn_s_barrier()
; #define PG8_SCHED __builtin_amdgcn_sched_barrier(0)
; template <class Epi, class Sched, bool F8 = false>
; __device__ __forceinline__ void gemm_phase(LAS unsigned char* lds, const int lda, const int ldb, const Sched& S, const Epi& E) {
;     ...
;             PG8_WAIT_V(8); PG8_WAIT_L(0); PG8_BAR; PG8_MMA(1, 0, At, B0); PG8_MMA(1, 1, At, B1); PG8_BAR; PG8_SCHED;
;             PG8_LDB(B0, 1, 0); PG8_LDB(B1, 1, 1); PG8_SCHED; PG8_LDA(At, 1, 0); PG8_STAGE(PG8_SA(0, 1), a2 + hstepA, voffA);
;             PG8_WAIT_V(8); PG8_WAIT_L(0); PG8_BAR; PG8_MMA(0, 0, At, B0); PG8_MMA(0, 1, At, B1); PG8_BAR; PG8_SCHED;
	s_setprio 1
	v_mfma_f32_16x16x32_bf16 v[60:63], v[136:139], v[184:187], v[60:63]
	v_mfma_f32_16x16x32_bf16 v[56:59], v[152:155], v[184:187], v[56:59]
	v_mfma_f32_16x16x32_bf16 v[44:47], v[136:139], v[194:197], v[44:47]
	v_mfma_f32_16x16x32_bf16 v[40:43], v[152:155], v[194:197], v[40:43]
	v_mfma_f32_16x16x32_bf16 v[28:31], v[136:139], v[202:205], v[28:31]
	v_mfma_f32_16x16x32_bf16 v[24:27], v[152:155], v[202:205], v[24:27]
	v_mfma_f32_16x16x32_bf16 v[12:15], v[136:139], v[210:213], v[12:15]
	v_mfma_f32_16x16x32_bf16 v[8:11], v[152:155], v[210:213], v[8:11]
	v_mfma_f32_16x16x32_bf16 v[60:63], v[148:151], v[188:191], v[60:63]
	v_mfma_f32_16x16x32_bf16 v[56:59], v[156:159], v[188:191], v[56:59]
	v_mfma_f32_16x16x32_bf16 v[44:47], v[148:151], v[198:201], v[44:47]
	v_mfma_f32_16x16x32_bf16 v[40:43], v[156:159], v[198:201], v[40:43]
	v_mfma_f32_16x16x32_bf16 v[28:31], v[148:151], v[206:209], v[28:31]
	v_mfma_f32_16x16x32_bf16 v[24:27], v[156:159], v[206:209], v[24:27]
	v_mfma_f32_16x16x32_bf16 v[12:15], v[148:151], v[214:217], v[12:15]
	v_mfma_f32_16x16x32_bf16 v[8:11], v[156:159], v[214:217], v[8:11]
	s_setprio 0
	s_setprio 1
	v_mfma_f32_16x16x32_bf16 v[52:55], v[160:163], v[184:187], v[52:55]
	v_mfma_f32_16x16x32_bf16 v[48:51], v[168:171], v[184:187], v[48:51]
	v_mfma_f32_16x16x32_bf16 v[36:39], v[160:163], v[194:197], v[36:39]
	v_mfma_f32_16x16x32_bf16 v[32:35], v[168:171], v[194:197], v[32:35]
	v_mfma_f32_16x16x32_bf16 v[20:23], v[160:163], v[202:205], v[20:23]
	v_mfma_f32_16x16x32_bf16 v[16:19], v[168:171], v[202:205], v[16:19]
	v_mfma_f32_16x16x32_bf16 v[4:7], v[160:163], v[210:213], v[4:7]
	v_mfma_f32_16x16x32_bf16 v[0:3], v[168:171], v[210:213], v[0:3]
	v_mfma_f32_16x16x32_bf16 v[52:55], v[164:167], v[188:191], v[52:55]
	v_mfma_f32_16x16x32_bf16 v[48:51], v[180:183], v[188:191], v[48:51]
	v_mfma_f32_16x16x32_bf16 v[36:39], v[164:167], v[198:201], v[36:39]
	v_mfma_f32_16x16x32_bf16 v[32:35], v[180:183], v[198:201], v[32:35]
	v_mfma_f32_16x16x32_bf16 v[20:23], v[164:167], v[206:209], v[20:23]
	v_mfma_f32_16x16x32_bf16 v[16:19], v[180:183], v[206:209], v[16:19]
	v_mfma_f32_16x16x32_bf16 v[4:7], v[164:167], v[214:217], v[4:7]
	v_mfma_f32_16x16x32_bf16 v[0:3], v[180:183], v[214:217], v[0:3]
	s_setprio 0
	s_barrier
	ds_read_b128 v[136:139], v145
	ds_read_b128 v[148:151], v145 offset:1024
	ds_read_b128 v[152:155], v145 offset:2048
	ds_read_b128 v[156:159], v145 offset:3072
	ds_read_b128 v[160:163], v146
	ds_read_b128 v[164:167], v146 offset:1024
	ds_read_b128 v[168:171], v146 offset:2048
	ds_read_b128 v[180:183], v146 offset:3072
	s_add_u32 s4, s20, 0x2b0000
	s_addc_u32 s5, s15, 0
	s_and_b32 s5, s5, 0xffff
	s_mov_b32 m0, s61
	ds_read_b128 v[184:187], v144 offset:32768
	ds_read_b128 v[188:191], v144 offset:33792
	ds_read_b128 v[194:197], v144 offset:34816
	ds_read_b128 v[198:201], v144 offset:35840
	ds_read_b128 v[202:205], v144 offset:36864
	ds_read_b128 v[206:209], v144 offset:37888
	ds_read_b128 v[210:213], v144 offset:38912
	ds_read_b128 v[214:217], v144 offset:39936
	buffer_load_dwordx4 v128, s[4:7], 0 offen lds
	s_mov_b32 m0, s66
	s_nop 0
	buffer_load_dwordx4 v130, s[4:7], 0 offen lds
	s_waitcnt vmcnt(8)
	s_waitcnt lgkmcnt(0)
	s_barrier
	s_setprio 1
	v_mfma_f32_16x16x32_bf16 v[124:127], v[136:139], v[184:187], v[124:127]
	v_mfma_f32_16x16x32_bf16 v[120:123], v[152:155], v[184:187], v[120:123]
	v_mfma_f32_16x16x32_bf16 v[108:111], v[136:139], v[194:197], v[108:111]
	v_mfma_f32_16x16x32_bf16 v[104:107], v[152:155], v[194:197], v[104:107]
	v_mfma_f32_16x16x32_bf16 v[92:95], v[136:139], v[202:205], v[92:95]
	v_mfma_f32_16x16x32_bf16 v[88:91], v[152:155], v[202:205], v[88:91]
	v_mfma_f32_16x16x32_bf16 v[76:79], v[136:139], v[210:213], v[76:79]
	v_mfma_f32_16x16x32_bf16 v[72:75], v[152:155], v[210:213], v[72:75]
	v_mfma_f32_16x16x32_bf16 v[124:127], v[148:151], v[188:191], v[124:127]
	v_mfma_f32_16x16x32_bf16 v[120:123], v[156:159], v[188:191], v[120:123]
	v_mfma_f32_16x16x32_bf16 v[108:111], v[148:151], v[198:201], v[108:111]
	v_mfma_f32_16x16x32_bf16 v[104:107], v[156:159], v[198:201], v[104:107]
	v_mfma_f32_16x16x32_bf16 v[92:95], v[148:151], v[206:209], v[92:95]
	v_mfma_f32_16x16x32_bf16 v[88:91], v[156:159], v[206:209], v[88:91]
	v_mfma_f32_16x16x32_bf16 v[76:79], v[148:151], v[214:217], v[76:79]
	v_mfma_f32_16x16x32_bf16 v[72:75], v[156:159], v[214:217], v[72:75]
	s_setprio 0
	s_setprio 1
	v_mfma_f32_16x16x32_bf16 v[116:119], v[160:163], v[184:187], v[116:119]
	v_mfma_f32_16x16x32_bf16 v[112:115], v[168:171], v[184:187], v[112:115]
	v_mfma_f32_16x16x32_bf16 v[100:103], v[160:163], v[194:197], v[100:103]
	v_mfma_f32_16x16x32_bf16 v[96:99], v[168:171], v[194:197], v[96:99]
	v_mfma_f32_16x16x32_bf16 v[84:87], v[160:163], v[202:205], v[84:87]
	v_mfma_f32_16x16x32_bf16 v[80:83], v[168:171], v[202:205], v[80:83]
	v_mfma_f32_16x16x32_bf16 v[68:71], v[160:163], v[210:213], v[68:71]
	v_mfma_f32_16x16x32_bf16 v[64:67], v[168:171], v[210:213], v[64:67]
	v_mfma_f32_16x16x32_bf16 v[116:119], v[164:167], v[188:191], v[116:119]
	v_mfma_f32_16x16x32_bf16 v[112:115], v[180:183], v[188:191], v[112:115]
	v_mfma_f32_16x16x32_bf16 v[100:103], v[164:167], v[198:201], v[100:103]
	v_mfma_f32_16x16x32_bf16 v[96:99], v[180:183], v[198:201], v[96:99]
	v_mfma_f32_16x16x32_bf16 v[84:87], v[164:167], v[206:209], v[84:87]
	v_mfma_f32_16x16x32_bf16 v[80:83], v[180:183], v[206:209], v[80:83]
	v_mfma_f32_16x16x32_bf16 v[68:71], v[164:167], v[214:217], v[68:71]
	v_mfma_f32_16x16x32_bf16 v[64:67], v[180:183], v[214:217], v[64:67]
	s_setprio 0
	s_barrier
; #define PG8_STAGE(bufoff, gbase, voff) do { const __amdgpu_buffer_rsrc_t _rs = __builtin_amdgcn_make_buffer_rsrc((void*)(gbase), 0, 0x7fffffff, 0x00020000); _Pragma("unroll") for (int _i = 0; _i < 2; ++_i) \
;         __builtin_amdgcn_raw_ptr_buffer_load_lds(_rs, (LAS unsigned*)(lds + (bufoff) + ldsw + _i * 8192), 16, (int)(voff)[_i], 0, 0, 0); } while (0)
; #define PG8_WAIT_V(n) asm volatile("s_waitcnt vmcnt(" #n ")" ::: "memory")
; #define PG8_WAIT_L(n) asm volatile("s_waitcnt lgkmcnt(" #n ")" ::: "memory")
; #define PG8_BAR __builtin_amdgcn_s_barrier()
; #define PG8_SCHED __builtin_amdgcn_sched_barrier(0)
; template <class Epi, class Sched, bool F8 = false>
; __device__ __forceinline__ void gemm_phase(LAS unsigned char* lds, const int lda, const int ldb, const Sched& S, const Epi& E) {
;     ...
;             PG8_LDA(At, 1, 1); PG8_STAGE(PG8_SB(1, 0), b3, voffB); PG8_STAGE(PG8_SB(1, 1), b3 + hstepB, voffB); PG8_STAGE(PG8_SA(1, 0), a3, voffA);
;             PG8_WAIT_V(8); PG8_WAIT_L(0); PG8_BAR; PG8_MMA(1, 0, At, B0); PG8_MMA(1, 1, At, B1); PG8_BAR; PG8_SCHED;
;     ...
;         }
;         if (wr == 0) PG8_BAR;
	s_add_u32 s4, s16, 0x8000
	s_addc_u32 s5, s14, 0
	s_mov_b32 m0, s73
	s_and_b32 s5, s5, 0xffff
	ds_read_b128 v[184:187], v144 offset:49152
	ds_read_b128 v[188:191], v144 offset:50176
	ds_read_b128 v[194:197], v144 offset:51200
	ds_read_b128 v[198:201], v144 offset:52224
	ds_read_b128 v[202:205], v144 offset:53248
	ds_read_b128 v[206:209], v144 offset:54272
	ds_read_b128 v[210:213], v144 offset:55296
	ds_read_b128 v[214:217], v144 offset:56320
	buffer_load_dwordx4 v129, s[4:7], 0 offen lds
	s_mov_b32 m0, s74
	s_mov_b32 s15, s7
	buffer_load_dwordx4 v131, s[4:7], 0 offen lds
	s_add_u32 s4, s16, 0xc000
	s_addc_u32 s5, s14, 0
	s_and_b32 s5, s5, 0xffff
	s_mov_b32 m0, s77
	s_and_b32 s13, s13, 0xffff
	buffer_load_dwordx4 v129, s[4:7], 0 offen lds
	s_mov_b32 m0, s78
	s_mov_b32 s14, s6
	buffer_load_dwordx4 v131, s[4:7], 0 offen lds
	s_mov_b32 m0, s75
	s_nop 0
	buffer_load_dwordx4 v128, s[12:15], 0 offen lds
	s_mov_b32 m0, s76
	s_nop 0
	buffer_load_dwordx4 v130, s[12:15], 0 offen lds
	s_waitcnt vmcnt(8)
	s_waitcnt lgkmcnt(0)
	s_barrier
	s_setprio 1
	v_mfma_f32_16x16x32_bf16 v[60:63], v[136:139], v[184:187], v[60:63]
	v_mfma_f32_16x16x32_bf16 v[56:59], v[152:155], v[184:187], v[56:59]
	v_mfma_f32_16x16x32_bf16 v[44:47], v[136:139], v[194:197], v[44:47]
	v_mfma_f32_16x16x32_bf16 v[40:43], v[152:155], v[194:197], v[40:43]
	v_mfma_f32_16x16x32_bf16 v[28:31], v[136:139], v[202:205], v[28:31]
	v_mfma_f32_16x16x32_bf16 v[24:27], v[152:155], v[202:205], v[24:27]
	v_mfma_f32_16x16x32_bf16 v[12:15], v[136:139], v[210:213], v[12:15]
	v_mfma_f32_16x16x32_bf16 v[8:11], v[152:155], v[210:213], v[8:11]
	v_mfma_f32_16x16x32_bf16 v[60:63], v[148:151], v[188:191], v[60:63]
	v_mfma_f32_16x16x32_bf16 v[56:59], v[156:159], v[188:191], v[56:59]
	v_mfma_f32_16x16x32_bf16 v[44:47], v[148:151], v[198:201], v[44:47]
	v_mfma_f32_16x16x32_bf16 v[40:43], v[156:159], v[198:201], v[40:43]
	v_mfma_f32_16x16x32_bf16 v[28:31], v[148:151], v[206:209], v[28:31]
	v_mfma_f32_16x16x32_bf16 v[24:27], v[156:159], v[206:209], v[24:27]
	v_mfma_f32_16x16x32_bf16 v[12:15], v[148:151], v[214:217], v[12:15]
	v_mfma_f32_16x16x32_bf16 v[8:11], v[156:159], v[214:217], v[8:11]
	s_setprio 0
	s_setprio 1
	v_mfma_f32_16x16x32_bf16 v[52:55], v[160:163], v[184:187], v[52:55]
	v_mfma_f32_16x16x32_bf16 v[48:51], v[168:171], v[184:187], v[48:51]
	v_mfma_f32_16x16x32_bf16 v[36:39], v[160:163], v[194:197], v[36:39]
	v_mfma_f32_16x16x32_bf16 v[32:35], v[168:171], v[194:197], v[32:35]
	v_mfma_f32_16x16x32_bf16 v[20:23], v[160:163], v[202:205], v[20:23]
	v_mfma_f32_16x16x32_bf16 v[16:19], v[168:171], v[202:205], v[16:19]
	v_mfma_f32_16x16x32_bf16 v[4:7], v[160:163], v[210:213], v[4:7]
	v_mfma_f32_16x16x32_bf16 v[0:3], v[168:171], v[210:213], v[0:3]
	v_mfma_f32_16x16x32_bf16 v[52:55], v[164:167], v[188:191], v[52:55]
	v_mfma_f32_16x16x32_bf16 v[48:51], v[180:183], v[188:191], v[48:51]
	v_mfma_f32_16x16x32_bf16 v[36:39], v[164:167], v[198:201], v[36:39]
	v_mfma_f32_16x16x32_bf16 v[32:35], v[180:183], v[198:201], v[32:35]
	v_mfma_f32_16x16x32_bf16 v[20:23], v[164:167], v[206:209], v[20:23]
	v_mfma_f32_16x16x32_bf16 v[16:19], v[180:183], v[206:209], v[16:19]
	v_mfma_f32_16x16x32_bf16 v[4:7], v[164:167], v[214:217], v[4:7]
	v_mfma_f32_16x16x32_bf16 v[0:3], v[180:183], v[214:217], v[0:3]
	s_setprio 0
	s_barrier
	s_add_i32 s64, s64, 2
	s_add_u32 s89, s89, 0x10000
	s_addc_u32 s90, s90, 0
	s_add_u32 s91, s91, 0x100
	s_addc_u32 s92, s92, 0
	s_cmpk_gt_u32 s64, 0xa9
	s_cbranch_scc0 .LBB0_935
	s_and_b64 vcc, exec, s[30:31]
	s_cbranch_vccz .LBB0_938
	s_barrier
